# P6/P11 epilogue: hoist the 8 serialized rmsnorm partial-sum loads to epilogue start (counted waits)
# baseline (speedup 1.0000x reference)
.LBB0_779:
	v_lshl_add_u32 v148, s4, 8, v150
	v_ashrrev_i32_e32 v149, 31, v148
	v_lshlrev_b64 v[146:147], 6, v[148:149]
	v_lshl_add_u64 v[146:147], v[136:137], 0, v[146:147]
	s_mov_b64 s[98:99], 0x2000
	global_load_dwordx4 v[160:163], v[146:147], off
	global_load_dwordx4 v[206:209], v[146:147], off offset:1024
	global_load_dwordx4 v[210:213], v[146:147], off offset:2048
	global_load_dwordx4 v[214:217], v[146:147], off offset:3072
	v_lshl_add_u64 v[234:235], v[146:147], 0, s[98:99]
	global_load_dwordx4 v[218:221], v[234:235], off
	global_load_dwordx4 v[222:225], v[234:235], off offset:1024
	global_load_dwordx4 v[226:229], v[234:235], off offset:2048
	global_load_dwordx4 v[230:233], v[234:235], off offset:3072
	v_and_b32_e32 v159, 64, v156
	v_xor_b32_e32 v147, 16, v156
	v_add_u32_e32 v167, 64, v159
	v_cmp_lt_i32_e32 vcc, v147, v167
	v_xor_b32_e32 v166, 32, v156
	v_lshl_or_b32 v146, s5, 8, v152
	v_cndmask_b32_e32 v147, v156, v147, vcc
	v_lshlrev_b32_e32 v159, 2, v147
	v_cmp_lt_i32_e32 vcc, v166, v167
	v_ashrrev_i32_e32 v147, 31, v146
	v_lshlrev_b64 v[146:147], 1, v[146:147]
	s_waitcnt vmcnt(7)
	v_mov_b32_e32 v164, v161
	v_mov_b32_e32 v165, v162
	v_mov_b32_e32 v161, v163
	v_pk_add_f32 v[160:161], v[164:165], v[160:161]
	v_lshlrev_b64 v[164:165], 13, v[148:149]
	v_add_f32_e32 v161, v160, v161
	ds_bpermute_b32 v162, v159, v161
	v_cndmask_b32_e32 v160, v156, v166, vcc
	v_lshlrev_b32_e32 v160, 2, v160
	v_lshl_add_u64 v[164:165], s[10:11], 0, v[164:165]
	v_lshl_add_u64 v[164:165], v[164:165], 0, v[146:147]
	s_waitcnt lgkmcnt(0)
	v_add_f32_e32 v161, v161, v162
	ds_bpermute_b32 v166, v160, v161
	v_or_b32_e32 v162, 16, v148
	v_ashrrev_i32_e32 v163, 31, v162
	s_waitcnt lgkmcnt(0)
	v_add_f32_e32 v149, v161, v166
	v_fmamk_f32 v149, v149, 0x3a800000, v157
	v_mul_f32_e32 v161, 0x4f800000, v149
	v_cmp_gt_f32_e32 vcc, s46, v149
	v_lshlrev_b64 v[166:167], 6, v[162:163]
	v_lshl_add_u64 v[166:167], v[136:137], 0, v[166:167]
	v_cndmask_b32_e32 v149, v149, v161, vcc
	v_sqrt_f32_e32 v161, v149
	s_nop 0
	v_add_u32_e32 v168, -1, v161
	v_add_u32_e32 v169, 1, v161
	v_fma_f32 v170, -v168, v161, v149
	v_fma_f32 v171, -v169, v161, v149
	v_cmp_ge_f32_e64 s[4:5], 0, v170
	s_nop 1
	v_cndmask_b32_e64 v161, v161, v168, s[4:5]
	v_cmp_lt_f32_e64 s[4:5], 0, v171
	s_nop 1
	v_cndmask_b32_e64 v161, v161, v169, s[4:5]
	v_mul_f32_e32 v168, 0x37800000, v161
	v_cndmask_b32_e32 v161, v161, v168, vcc
	v_cmp_class_f32_e32 vcc, v149, v158
	s_nop 1
	v_cndmask_b32_e32 v149, v161, v149, vcc
	v_div_scale_f32 v161, s[4:5], v149, v149, 1.0
	v_rcp_f32_e32 v168, v161
	v_div_scale_f32 v169, vcc, 1.0, v149, 1.0
	v_fma_f32 v170, -v161, v168, 1.0
	v_fmac_f32_e32 v168, v170, v168
	v_mul_f32_e32 v170, v169, v168
	v_fma_f32 v171, -v161, v170, v169
	v_fmac_f32_e32 v170, v171, v168
	v_fma_f32 v161, -v161, v170, v169
	v_div_fmas_f32 v161, v161, v168, v170
	v_div_fixup_f32 v168, v161, v149, 1.0
	v_pk_mul_f32 v[126:127], v[126:127], v[168:169] op_sel_hi:[1,0]
	v_pk_mul_f32 v[124:125], v[124:125], v[168:169] op_sel_hi:[1,0]
	v_pk_mul_f32 v[122:123], v[122:123], v[168:169] op_sel_hi:[1,0]
	v_pk_mul_f32 v[120:121], v[120:121], v[168:169] op_sel_hi:[1,0]
	v_pk_mul_f32 v[114:115], v[114:115], v[168:169] op_sel_hi:[1,0]
	v_pk_mul_f32 v[112:113], v[112:113], v[168:169] op_sel_hi:[1,0]
	v_pk_mul_f32 v[118:119], v[118:119], v[168:169] op_sel_hi:[1,0]
	v_pk_mul_f32 v[116:117], v[116:117], v[168:169] op_sel_hi:[1,0]
	v_max_f32_e32 v124, 0, v124
	v_max_f32_e32 v120, 0, v120
	v_max_f32_e32 v125, 0, v125
	v_max_f32_e32 v121, 0, v121
	v_max_f32_e32 v126, 0, v126
	v_max_f32_e32 v122, 0, v122
	v_max_f32_e32 v127, 0, v127
	v_max_f32_e32 v123, 0, v123
	v_max_f32_e32 v112, 0, v112
	v_max_f32_e32 v113, 0, v113
	v_max_f32_e32 v114, 0, v114
	v_max_f32_e32 v115, 0, v115
	v_max_f32_e32 v116, 0, v116
	v_max_f32_e32 v117, 0, v117
	v_max_f32_e32 v118, 0, v118
	v_max_f32_e32 v119, 0, v119
	v_mul_f32_e32 v124, v124, v124
	v_mul_f32_e32 v120, v120, v120
	v_mul_f32_e32 v125, v125, v125
	v_mul_f32_e32 v121, v121, v121
	v_mul_f32_e32 v126, v126, v126
	v_mul_f32_e32 v122, v122, v122
	v_mul_f32_e32 v127, v127, v127
	v_mul_f32_e32 v123, v123, v123
	v_mul_f32_e32 v149, v112, v112
	v_mul_f32_e32 v161, v113, v113
	v_mul_f32_e32 v168, v114, v114
	v_mul_f32_e32 v169, v115, v115
	v_cvt_pk_bf16_f32 v112, v124, v125
	v_cvt_pk_bf16_f32 v113, v126, v127
	v_cvt_pk_bf16_f32 v114, v120, v121
	v_cvt_pk_bf16_f32 v115, v122, v123
	v_mul_f32_e32 v116, v116, v116
	v_mul_f32_e32 v117, v117, v117
	v_mul_f32_e32 v118, v118, v118
	v_mul_f32_e32 v119, v119, v119
	global_store_dwordx4 v[164:165], v[112:115], off
	s_nop 1
	v_cvt_pk_bf16_f32 v112, v116, v117
	v_cvt_pk_bf16_f32 v113, v118, v119
	v_cvt_pk_bf16_f32 v114, v149, v161
	v_cvt_pk_bf16_f32 v115, v168, v169
	global_store_dwordx4 v[164:165], v[112:115], off offset:256
	s_waitcnt vmcnt(8)
	s_nop 1
	v_mov_b32_e32 v112, v206
	v_mov_b32_e32 v113, v207
	v_mov_b32_e32 v114, v208
	v_mov_b32_e32 v115, v209
	v_mov_b32_e32 v116, v113
	v_mov_b32_e32 v117, v114
	v_mov_b32_e32 v113, v115
	v_pk_add_f32 v[112:113], v[116:117], v[112:113]
	v_lshlrev_b64 v[114:115], 13, v[162:163]
	v_add_f32_e32 v112, v112, v113
	ds_bpermute_b32 v113, v159, v112
	v_lshl_add_u64 v[114:115], s[10:11], 0, v[114:115]
	v_lshl_add_u64 v[114:115], v[114:115], 0, v[146:147]
	s_waitcnt lgkmcnt(0)
	v_add_f32_e32 v116, v112, v113
	ds_bpermute_b32 v117, v160, v116
	v_or_b32_e32 v112, 32, v148
	v_ashrrev_i32_e32 v113, 31, v112
	s_waitcnt lgkmcnt(0)
	v_add_f32_e32 v116, v116, v117
	v_fmamk_f32 v116, v116, 0x3a800000, v157
	v_mul_f32_e32 v117, 0x4f800000, v116
	v_cmp_gt_f32_e32 vcc, s46, v116
	s_nop 1
	v_cndmask_b32_e32 v118, v116, v117, vcc
	v_sqrt_f32_e32 v119, v118
	v_lshlrev_b64 v[116:117], 6, v[112:113]
	v_lshl_add_u64 v[116:117], v[136:137], 0, v[116:117]
	v_add_u32_e32 v120, -1, v119
	v_add_u32_e32 v121, 1, v119
	v_fma_f32 v122, -v120, v119, v118
	v_fma_f32 v123, -v121, v119, v118
	v_cmp_ge_f32_e64 s[4:5], 0, v122
	s_nop 1
	v_cndmask_b32_e64 v119, v119, v120, s[4:5]
	v_cmp_lt_f32_e64 s[4:5], 0, v123
	s_nop 1
	v_cndmask_b32_e64 v119, v119, v121, s[4:5]
	v_mul_f32_e32 v120, 0x37800000, v119
	v_cndmask_b32_e32 v119, v119, v120, vcc
	v_cmp_class_f32_e32 vcc, v118, v158
	s_nop 1
	v_cndmask_b32_e32 v118, v119, v118, vcc
	v_div_scale_f32 v119, s[4:5], v118, v118, 1.0
	v_rcp_f32_e32 v120, v119
	v_div_scale_f32 v121, vcc, 1.0, v118, 1.0
	v_fma_f32 v122, -v119, v120, 1.0
	v_fmac_f32_e32 v120, v122, v120
	v_mul_f32_e32 v122, v121, v120
	v_fma_f32 v123, -v119, v122, v121
	v_fmac_f32_e32 v122, v123, v120
	v_fma_f32 v119, -v119, v122, v121
	v_div_fmas_f32 v119, v119, v120, v122
	v_div_fixup_f32 v118, v119, v118, 1.0
	v_pk_mul_f32 v[110:111], v[110:111], v[118:119] op_sel_hi:[1,0]
	v_pk_mul_f32 v[108:109], v[108:109], v[118:119] op_sel_hi:[1,0]
	v_pk_mul_f32 v[106:107], v[106:107], v[118:119] op_sel_hi:[1,0]
	v_pk_mul_f32 v[104:105], v[104:105], v[118:119] op_sel_hi:[1,0]
	v_pk_mul_f32 v[98:99], v[98:99], v[118:119] op_sel_hi:[1,0]
	v_pk_mul_f32 v[96:97], v[96:97], v[118:119] op_sel_hi:[1,0]
	v_pk_mul_f32 v[102:103], v[102:103], v[118:119] op_sel_hi:[1,0]
	v_pk_mul_f32 v[100:101], v[100:101], v[118:119] op_sel_hi:[1,0]
	v_max_f32_e32 v108, 0, v108
	v_max_f32_e32 v104, 0, v104
	v_max_f32_e32 v109, 0, v109
	v_max_f32_e32 v105, 0, v105
	v_max_f32_e32 v110, 0, v110
	v_max_f32_e32 v106, 0, v106
	v_max_f32_e32 v111, 0, v111
	v_max_f32_e32 v107, 0, v107
	v_max_f32_e32 v96, 0, v96
	v_max_f32_e32 v97, 0, v97
	v_max_f32_e32 v98, 0, v98
	v_max_f32_e32 v99, 0, v99
	v_max_f32_e32 v100, 0, v100
	v_max_f32_e32 v101, 0, v101
	v_max_f32_e32 v102, 0, v102
	v_max_f32_e32 v103, 0, v103
	v_mul_f32_e32 v108, v108, v108
	v_mul_f32_e32 v104, v104, v104
	v_mul_f32_e32 v109, v109, v109
	v_mul_f32_e32 v105, v105, v105
	v_mul_f32_e32 v110, v110, v110
	v_mul_f32_e32 v106, v106, v106
	v_mul_f32_e32 v111, v111, v111
	v_mul_f32_e32 v107, v107, v107
	v_mul_f32_e32 v118, v96, v96
	v_mul_f32_e32 v119, v97, v97
	v_mul_f32_e32 v120, v98, v98
	v_mul_f32_e32 v121, v99, v99
	v_cvt_pk_bf16_f32 v96, v108, v109
	v_cvt_pk_bf16_f32 v97, v110, v111
	v_cvt_pk_bf16_f32 v98, v104, v105
	v_cvt_pk_bf16_f32 v99, v106, v107
	v_mul_f32_e32 v100, v100, v100
	v_mul_f32_e32 v101, v101, v101
	v_mul_f32_e32 v102, v102, v102
	v_mul_f32_e32 v103, v103, v103
	global_store_dwordx4 v[114:115], v[96:99], off
	s_nop 1
	v_cvt_pk_bf16_f32 v96, v100, v101
	v_cvt_pk_bf16_f32 v97, v102, v103
	v_cvt_pk_bf16_f32 v98, v118, v119
	v_cvt_pk_bf16_f32 v99, v120, v121
	global_store_dwordx4 v[114:115], v[96:99], off offset:256
	s_waitcnt vmcnt(9)
	s_nop 1
	v_mov_b32_e32 v96, v210
	v_mov_b32_e32 v97, v211
	v_mov_b32_e32 v98, v212
	v_mov_b32_e32 v99, v213
	v_mov_b32_e32 v100, v97
	v_mov_b32_e32 v101, v98
	v_mov_b32_e32 v97, v99
	v_pk_add_f32 v[96:97], v[100:101], v[96:97]
	v_lshlrev_b64 v[98:99], 13, v[112:113]
	v_add_f32_e32 v96, v96, v97
	ds_bpermute_b32 v97, v159, v96
	v_lshl_add_u64 v[98:99], s[10:11], 0, v[98:99]
	v_lshl_add_u64 v[98:99], v[98:99], 0, v[146:147]
	s_waitcnt lgkmcnt(0)
	v_add_f32_e32 v100, v96, v97
	ds_bpermute_b32 v101, v160, v100
	v_or_b32_e32 v96, 48, v148
	v_ashrrev_i32_e32 v97, 31, v96
	s_waitcnt lgkmcnt(0)
	v_add_f32_e32 v100, v100, v101
	v_fmamk_f32 v100, v100, 0x3a800000, v157
	v_mul_f32_e32 v101, 0x4f800000, v100
	v_cmp_gt_f32_e32 vcc, s46, v100
	s_nop 1
	v_cndmask_b32_e32 v102, v100, v101, vcc
	v_sqrt_f32_e32 v103, v102
	v_lshlrev_b64 v[100:101], 6, v[96:97]
	v_lshl_add_u64 v[100:101], v[136:137], 0, v[100:101]
	v_add_u32_e32 v104, -1, v103
	v_add_u32_e32 v105, 1, v103
	v_fma_f32 v106, -v104, v103, v102
	v_fma_f32 v107, -v105, v103, v102
	v_cmp_ge_f32_e64 s[4:5], 0, v106
	s_nop 1
	v_cndmask_b32_e64 v103, v103, v104, s[4:5]
	v_cmp_lt_f32_e64 s[4:5], 0, v107
	s_nop 1
	v_cndmask_b32_e64 v103, v103, v105, s[4:5]
	v_mul_f32_e32 v104, 0x37800000, v103
	v_cndmask_b32_e32 v103, v103, v104, vcc
	v_cmp_class_f32_e32 vcc, v102, v158
	s_nop 1
	v_cndmask_b32_e32 v102, v103, v102, vcc
	v_div_scale_f32 v103, s[4:5], v102, v102, 1.0
	v_rcp_f32_e32 v104, v103
	v_div_scale_f32 v105, vcc, 1.0, v102, 1.0
	v_fma_f32 v106, -v103, v104, 1.0
	v_fmac_f32_e32 v104, v106, v104
	v_mul_f32_e32 v106, v105, v104
	v_fma_f32 v107, -v103, v106, v105
	v_fmac_f32_e32 v106, v107, v104
	v_fma_f32 v103, -v103, v106, v105
	v_div_fmas_f32 v103, v103, v104, v106
	v_div_fixup_f32 v102, v103, v102, 1.0
	v_pk_mul_f32 v[94:95], v[94:95], v[102:103] op_sel_hi:[1,0]
	v_pk_mul_f32 v[92:93], v[92:93], v[102:103] op_sel_hi:[1,0]
	v_pk_mul_f32 v[90:91], v[90:91], v[102:103] op_sel_hi:[1,0]
	v_pk_mul_f32 v[88:89], v[88:89], v[102:103] op_sel_hi:[1,0]
	v_pk_mul_f32 v[82:83], v[82:83], v[102:103] op_sel_hi:[1,0]
	v_pk_mul_f32 v[80:81], v[80:81], v[102:103] op_sel_hi:[1,0]
	v_pk_mul_f32 v[86:87], v[86:87], v[102:103] op_sel_hi:[1,0]
	v_pk_mul_f32 v[84:85], v[84:85], v[102:103] op_sel_hi:[1,0]
	v_max_f32_e32 v92, 0, v92
	v_max_f32_e32 v88, 0, v88
	v_max_f32_e32 v93, 0, v93
	v_max_f32_e32 v89, 0, v89
	v_max_f32_e32 v94, 0, v94
	v_max_f32_e32 v90, 0, v90
	v_max_f32_e32 v95, 0, v95
	v_max_f32_e32 v91, 0, v91
	v_max_f32_e32 v80, 0, v80
	v_max_f32_e32 v81, 0, v81
	v_max_f32_e32 v82, 0, v82
	v_max_f32_e32 v83, 0, v83
	v_max_f32_e32 v84, 0, v84
	v_max_f32_e32 v85, 0, v85
	v_max_f32_e32 v86, 0, v86
	v_max_f32_e32 v87, 0, v87
	v_mul_f32_e32 v92, v92, v92
	v_mul_f32_e32 v88, v88, v88
	v_mul_f32_e32 v93, v93, v93
	v_mul_f32_e32 v89, v89, v89
	v_mul_f32_e32 v94, v94, v94
	v_mul_f32_e32 v90, v90, v90
	v_mul_f32_e32 v95, v95, v95
	v_mul_f32_e32 v91, v91, v91
	v_mul_f32_e32 v102, v80, v80
	v_mul_f32_e32 v103, v81, v81
	v_mul_f32_e32 v104, v82, v82
	v_mul_f32_e32 v105, v83, v83
	v_cvt_pk_bf16_f32 v80, v92, v93
	v_cvt_pk_bf16_f32 v81, v94, v95
	v_cvt_pk_bf16_f32 v82, v88, v89
	v_cvt_pk_bf16_f32 v83, v90, v91
	v_mul_f32_e32 v84, v84, v84
	v_mul_f32_e32 v85, v85, v85
	v_mul_f32_e32 v86, v86, v86
	v_mul_f32_e32 v87, v87, v87
	global_store_dwordx4 v[98:99], v[80:83], off
	s_nop 1
	v_cvt_pk_bf16_f32 v80, v84, v85
	v_cvt_pk_bf16_f32 v81, v86, v87
	v_cvt_pk_bf16_f32 v82, v102, v103
	v_cvt_pk_bf16_f32 v83, v104, v105
	global_store_dwordx4 v[98:99], v[80:83], off offset:256
	s_waitcnt vmcnt(10)
	s_nop 1
	v_mov_b32_e32 v80, v214
	v_mov_b32_e32 v81, v215
	v_mov_b32_e32 v82, v216
	v_mov_b32_e32 v83, v217
	v_mov_b32_e32 v84, v81
	v_mov_b32_e32 v85, v82
	v_mov_b32_e32 v81, v83
	v_pk_add_f32 v[80:81], v[84:85], v[80:81]
	v_lshlrev_b64 v[82:83], 13, v[96:97]
	v_add_f32_e32 v80, v80, v81
	ds_bpermute_b32 v81, v159, v80
	v_lshl_add_u64 v[82:83], s[10:11], 0, v[82:83]
	v_lshl_add_u64 v[82:83], v[82:83], 0, v[146:147]
	s_waitcnt lgkmcnt(0)
	v_add_f32_e32 v84, v80, v81
	ds_bpermute_b32 v85, v160, v84
	v_add_u32_e32 v80, 0x80, v148
	v_ashrrev_i32_e32 v81, 31, v80
	s_waitcnt lgkmcnt(0)
	v_add_f32_e32 v84, v84, v85
	v_fmamk_f32 v84, v84, 0x3a800000, v157
	v_mul_f32_e32 v85, 0x4f800000, v84
	v_cmp_gt_f32_e32 vcc, s46, v84
	s_nop 1
	v_cndmask_b32_e32 v86, v84, v85, vcc
	v_sqrt_f32_e32 v87, v86
	v_lshlrev_b64 v[84:85], 6, v[80:81]
	v_lshl_add_u64 v[84:85], v[136:137], 0, v[84:85]
	v_add_u32_e32 v88, -1, v87
	v_add_u32_e32 v89, 1, v87
	v_fma_f32 v90, -v88, v87, v86
	v_fma_f32 v91, -v89, v87, v86
	v_cmp_ge_f32_e64 s[4:5], 0, v90
	s_nop 1
	v_cndmask_b32_e64 v87, v87, v88, s[4:5]
	v_cmp_lt_f32_e64 s[4:5], 0, v91
	s_nop 1
	v_cndmask_b32_e64 v87, v87, v89, s[4:5]
	v_mul_f32_e32 v88, 0x37800000, v87
	v_cndmask_b32_e32 v87, v87, v88, vcc
	v_cmp_class_f32_e32 vcc, v86, v158
	s_nop 1
	v_cndmask_b32_e32 v86, v87, v86, vcc
	v_div_scale_f32 v87, s[4:5], v86, v86, 1.0
	v_rcp_f32_e32 v88, v87
	v_div_scale_f32 v89, vcc, 1.0, v86, 1.0
	v_fma_f32 v90, -v87, v88, 1.0
	v_fmac_f32_e32 v88, v90, v88
	v_mul_f32_e32 v90, v89, v88
	v_fma_f32 v91, -v87, v90, v89
	v_fmac_f32_e32 v90, v91, v88
	v_fma_f32 v87, -v87, v90, v89
	v_div_fmas_f32 v87, v87, v88, v90
	v_div_fixup_f32 v86, v87, v86, 1.0
	v_pk_mul_f32 v[78:79], v[78:79], v[86:87] op_sel_hi:[1,0]
	v_pk_mul_f32 v[76:77], v[76:77], v[86:87] op_sel_hi:[1,0]
	v_pk_mul_f32 v[74:75], v[74:75], v[86:87] op_sel_hi:[1,0]
	v_pk_mul_f32 v[72:73], v[72:73], v[86:87] op_sel_hi:[1,0]
	v_pk_mul_f32 v[66:67], v[66:67], v[86:87] op_sel_hi:[1,0]
	v_pk_mul_f32 v[64:65], v[64:65], v[86:87] op_sel_hi:[1,0]
	v_pk_mul_f32 v[70:71], v[70:71], v[86:87] op_sel_hi:[1,0]
	v_pk_mul_f32 v[68:69], v[68:69], v[86:87] op_sel_hi:[1,0]
	v_max_f32_e32 v76, 0, v76
	v_max_f32_e32 v72, 0, v72
	v_max_f32_e32 v77, 0, v77
	v_max_f32_e32 v73, 0, v73
	v_max_f32_e32 v78, 0, v78
	v_max_f32_e32 v74, 0, v74
	v_max_f32_e32 v79, 0, v79
	v_max_f32_e32 v75, 0, v75
	v_max_f32_e32 v64, 0, v64
	v_max_f32_e32 v65, 0, v65
	v_max_f32_e32 v66, 0, v66
	v_max_f32_e32 v67, 0, v67
	v_max_f32_e32 v68, 0, v68
	v_max_f32_e32 v69, 0, v69
	v_max_f32_e32 v70, 0, v70
	v_max_f32_e32 v71, 0, v71
	v_mul_f32_e32 v76, v76, v76
	v_mul_f32_e32 v72, v72, v72
	v_mul_f32_e32 v77, v77, v77
	v_mul_f32_e32 v73, v73, v73
	v_mul_f32_e32 v78, v78, v78
	v_mul_f32_e32 v74, v74, v74
	v_mul_f32_e32 v79, v79, v79
	v_mul_f32_e32 v75, v75, v75
	v_mul_f32_e32 v86, v64, v64
	v_mul_f32_e32 v87, v65, v65
	v_mul_f32_e32 v88, v66, v66
	v_mul_f32_e32 v89, v67, v67
	v_cvt_pk_bf16_f32 v64, v76, v77
	v_cvt_pk_bf16_f32 v65, v78, v79
	v_cvt_pk_bf16_f32 v66, v72, v73
	v_cvt_pk_bf16_f32 v67, v74, v75
	v_mul_f32_e32 v68, v68, v68
	v_mul_f32_e32 v69, v69, v69
	v_mul_f32_e32 v70, v70, v70
	v_mul_f32_e32 v71, v71, v71
	global_store_dwordx4 v[82:83], v[64:67], off
	s_nop 1
	v_cvt_pk_bf16_f32 v64, v68, v69
	v_cvt_pk_bf16_f32 v65, v70, v71
	v_cvt_pk_bf16_f32 v66, v86, v87
	v_cvt_pk_bf16_f32 v67, v88, v89
	global_store_dwordx4 v[82:83], v[64:67], off offset:256
	s_waitcnt vmcnt(11)
	s_nop 1
	v_mov_b32_e32 v64, v218
	v_mov_b32_e32 v65, v219
	v_mov_b32_e32 v66, v220
	v_mov_b32_e32 v67, v221
	v_mov_b32_e32 v68, v65
	v_mov_b32_e32 v69, v66
	v_mov_b32_e32 v65, v67
	v_pk_add_f32 v[64:65], v[68:69], v[64:65]
	v_lshlrev_b64 v[66:67], 13, v[80:81]
	v_add_f32_e32 v64, v64, v65
	ds_bpermute_b32 v65, v159, v64
	v_lshl_add_u64 v[66:67], s[10:11], 0, v[66:67]
	v_lshl_add_u64 v[66:67], v[66:67], 0, v[146:147]
	s_waitcnt lgkmcnt(0)
	v_add_f32_e32 v68, v64, v65
	ds_bpermute_b32 v69, v160, v68
	v_add_u32_e32 v64, 0x90, v148
	v_ashrrev_i32_e32 v65, 31, v64
	s_waitcnt lgkmcnt(0)
	v_add_f32_e32 v68, v68, v69
	v_fmamk_f32 v68, v68, 0x3a800000, v157
	v_mul_f32_e32 v69, 0x4f800000, v68
	v_cmp_gt_f32_e32 vcc, s46, v68
	s_nop 1
	v_cndmask_b32_e32 v70, v68, v69, vcc
	v_sqrt_f32_e32 v71, v70
	v_lshlrev_b64 v[68:69], 6, v[64:65]
	v_lshl_add_u64 v[68:69], v[136:137], 0, v[68:69]
	v_add_u32_e32 v72, -1, v71
	v_add_u32_e32 v73, 1, v71
	v_fma_f32 v74, -v72, v71, v70
	v_fma_f32 v75, -v73, v71, v70
	v_cmp_ge_f32_e64 s[4:5], 0, v74
	s_nop 1
	v_cndmask_b32_e64 v71, v71, v72, s[4:5]
	v_cmp_lt_f32_e64 s[4:5], 0, v75
	s_nop 1
	v_cndmask_b32_e64 v71, v71, v73, s[4:5]
	v_mul_f32_e32 v72, 0x37800000, v71
	v_cndmask_b32_e32 v71, v71, v72, vcc
	v_cmp_class_f32_e32 vcc, v70, v158
	s_nop 1
	v_cndmask_b32_e32 v70, v71, v70, vcc
	v_div_scale_f32 v71, s[4:5], v70, v70, 1.0
	v_rcp_f32_e32 v72, v71
	v_div_scale_f32 v73, vcc, 1.0, v70, 1.0
	v_fma_f32 v74, -v71, v72, 1.0
	v_fmac_f32_e32 v72, v74, v72
	v_mul_f32_e32 v74, v73, v72
	v_fma_f32 v75, -v71, v74, v73
	v_fmac_f32_e32 v74, v75, v72
	v_fma_f32 v71, -v71, v74, v73
	v_div_fmas_f32 v71, v71, v72, v74
	v_div_fixup_f32 v70, v71, v70, 1.0
	v_pk_mul_f32 v[62:63], v[62:63], v[70:71] op_sel_hi:[1,0]
	v_pk_mul_f32 v[60:61], v[60:61], v[70:71] op_sel_hi:[1,0]
	v_pk_mul_f32 v[58:59], v[58:59], v[70:71] op_sel_hi:[1,0]
	v_pk_mul_f32 v[56:57], v[56:57], v[70:71] op_sel_hi:[1,0]
	v_pk_mul_f32 v[50:51], v[50:51], v[70:71] op_sel_hi:[1,0]
	v_pk_mul_f32 v[48:49], v[48:49], v[70:71] op_sel_hi:[1,0]
	v_pk_mul_f32 v[54:55], v[54:55], v[70:71] op_sel_hi:[1,0]
	v_pk_mul_f32 v[52:53], v[52:53], v[70:71] op_sel_hi:[1,0]
	v_max_f32_e32 v60, 0, v60
	v_max_f32_e32 v56, 0, v56
	v_max_f32_e32 v61, 0, v61
	v_max_f32_e32 v57, 0, v57
	v_max_f32_e32 v62, 0, v62
	v_max_f32_e32 v58, 0, v58
	v_max_f32_e32 v63, 0, v63
	v_max_f32_e32 v59, 0, v59
	v_max_f32_e32 v48, 0, v48
	v_max_f32_e32 v49, 0, v49
	v_max_f32_e32 v50, 0, v50
	v_max_f32_e32 v51, 0, v51
	v_max_f32_e32 v52, 0, v52
	v_max_f32_e32 v53, 0, v53
	v_max_f32_e32 v54, 0, v54
	v_max_f32_e32 v55, 0, v55
	v_mul_f32_e32 v60, v60, v60
	v_mul_f32_e32 v56, v56, v56
	v_mul_f32_e32 v61, v61, v61
	v_mul_f32_e32 v57, v57, v57
	v_mul_f32_e32 v62, v62, v62
	v_mul_f32_e32 v58, v58, v58
	v_mul_f32_e32 v63, v63, v63
	v_mul_f32_e32 v59, v59, v59
	v_mul_f32_e32 v70, v48, v48
	v_mul_f32_e32 v71, v49, v49
	v_mul_f32_e32 v72, v50, v50
	v_mul_f32_e32 v73, v51, v51
	v_cvt_pk_bf16_f32 v48, v60, v61
	v_cvt_pk_bf16_f32 v49, v62, v63
	v_cvt_pk_bf16_f32 v50, v56, v57
	v_cvt_pk_bf16_f32 v51, v58, v59
	v_mul_f32_e32 v52, v52, v52
	v_mul_f32_e32 v53, v53, v53
	v_mul_f32_e32 v54, v54, v54
	v_mul_f32_e32 v55, v55, v55
	global_store_dwordx4 v[66:67], v[48:51], off
	s_nop 1
	v_cvt_pk_bf16_f32 v48, v52, v53
	v_cvt_pk_bf16_f32 v49, v54, v55
	v_cvt_pk_bf16_f32 v50, v70, v71
	v_cvt_pk_bf16_f32 v51, v72, v73
	global_store_dwordx4 v[66:67], v[48:51], off offset:256
	s_waitcnt vmcnt(12)
	s_nop 1
	v_mov_b32_e32 v48, v222
	v_mov_b32_e32 v49, v223
	v_mov_b32_e32 v50, v224
	v_mov_b32_e32 v51, v225
	v_mov_b32_e32 v52, v49
	v_mov_b32_e32 v53, v50
	v_mov_b32_e32 v49, v51
	v_pk_add_f32 v[48:49], v[52:53], v[48:49]
	v_lshlrev_b64 v[50:51], 13, v[64:65]
	v_add_f32_e32 v48, v48, v49
	ds_bpermute_b32 v49, v159, v48
	v_lshl_add_u64 v[50:51], s[10:11], 0, v[50:51]
	v_lshl_add_u64 v[50:51], v[50:51], 0, v[146:147]
	s_waitcnt lgkmcnt(0)
	v_add_f32_e32 v52, v48, v49
	ds_bpermute_b32 v53, v160, v52
	v_add_u32_e32 v48, 0xa0, v148
	v_ashrrev_i32_e32 v49, 31, v48
	s_waitcnt lgkmcnt(0)
	v_add_f32_e32 v52, v52, v53
	v_fmamk_f32 v52, v52, 0x3a800000, v157
	v_mul_f32_e32 v53, 0x4f800000, v52
	v_cmp_gt_f32_e32 vcc, s46, v52
	s_nop 1
	v_cndmask_b32_e32 v54, v52, v53, vcc
	v_sqrt_f32_e32 v55, v54
	v_lshlrev_b64 v[52:53], 6, v[48:49]
	v_lshl_add_u64 v[52:53], v[136:137], 0, v[52:53]
	v_add_u32_e32 v56, -1, v55
	v_add_u32_e32 v57, 1, v55
	v_fma_f32 v58, -v56, v55, v54
	v_fma_f32 v59, -v57, v55, v54
	v_cmp_ge_f32_e64 s[4:5], 0, v58
	s_nop 1
	v_cndmask_b32_e64 v55, v55, v56, s[4:5]
	v_cmp_lt_f32_e64 s[4:5], 0, v59
	s_nop 1
	v_cndmask_b32_e64 v55, v55, v57, s[4:5]
	v_mul_f32_e32 v56, 0x37800000, v55
	v_cndmask_b32_e32 v55, v55, v56, vcc
	v_cmp_class_f32_e32 vcc, v54, v158
	s_nop 1
	v_cndmask_b32_e32 v54, v55, v54, vcc
	v_div_scale_f32 v55, s[4:5], v54, v54, 1.0
	v_rcp_f32_e32 v56, v55
	v_div_scale_f32 v57, vcc, 1.0, v54, 1.0
	v_fma_f32 v58, -v55, v56, 1.0
	v_fmac_f32_e32 v56, v58, v56
	v_mul_f32_e32 v58, v57, v56
	v_fma_f32 v59, -v55, v58, v57
	v_fmac_f32_e32 v58, v59, v56
	v_fma_f32 v55, -v55, v58, v57
	v_div_fmas_f32 v55, v55, v56, v58
	v_div_fixup_f32 v54, v55, v54, 1.0
	v_pk_mul_f32 v[46:47], v[46:47], v[54:55] op_sel_hi:[1,0]
	v_pk_mul_f32 v[44:45], v[44:45], v[54:55] op_sel_hi:[1,0]
	v_pk_mul_f32 v[42:43], v[42:43], v[54:55] op_sel_hi:[1,0]
	v_pk_mul_f32 v[40:41], v[40:41], v[54:55] op_sel_hi:[1,0]
	v_pk_mul_f32 v[34:35], v[34:35], v[54:55] op_sel_hi:[1,0]
	v_pk_mul_f32 v[32:33], v[32:33], v[54:55] op_sel_hi:[1,0]
	v_pk_mul_f32 v[38:39], v[38:39], v[54:55] op_sel_hi:[1,0]
	v_pk_mul_f32 v[36:37], v[36:37], v[54:55] op_sel_hi:[1,0]
	v_max_f32_e32 v44, 0, v44
	v_max_f32_e32 v40, 0, v40
	v_max_f32_e32 v45, 0, v45
	v_max_f32_e32 v41, 0, v41
	v_max_f32_e32 v46, 0, v46
	v_max_f32_e32 v42, 0, v42
	v_max_f32_e32 v47, 0, v47
	v_max_f32_e32 v43, 0, v43
	v_max_f32_e32 v32, 0, v32
	v_max_f32_e32 v33, 0, v33
	v_max_f32_e32 v34, 0, v34
	v_max_f32_e32 v35, 0, v35
	v_max_f32_e32 v36, 0, v36
	v_max_f32_e32 v37, 0, v37
	v_max_f32_e32 v38, 0, v38
	v_max_f32_e32 v39, 0, v39
	v_mul_f32_e32 v44, v44, v44
	v_mul_f32_e32 v40, v40, v40
	v_mul_f32_e32 v45, v45, v45
	v_mul_f32_e32 v41, v41, v41
	v_mul_f32_e32 v46, v46, v46
	v_mul_f32_e32 v42, v42, v42
	v_mul_f32_e32 v47, v47, v47
	v_mul_f32_e32 v43, v43, v43
	v_mul_f32_e32 v54, v32, v32
	v_mul_f32_e32 v55, v33, v33
	v_mul_f32_e32 v56, v34, v34
	v_mul_f32_e32 v57, v35, v35
	v_cvt_pk_bf16_f32 v32, v44, v45
	v_cvt_pk_bf16_f32 v33, v46, v47
	v_cvt_pk_bf16_f32 v34, v40, v41
	v_cvt_pk_bf16_f32 v35, v42, v43
	v_mul_f32_e32 v36, v36, v36
	v_mul_f32_e32 v37, v37, v37
	v_mul_f32_e32 v38, v38, v38
	v_mul_f32_e32 v39, v39, v39
	global_store_dwordx4 v[50:51], v[32:35], off
	s_nop 1
	v_cvt_pk_bf16_f32 v32, v36, v37
	v_cvt_pk_bf16_f32 v33, v38, v39
	v_cvt_pk_bf16_f32 v34, v54, v55
	v_cvt_pk_bf16_f32 v35, v56, v57
	global_store_dwordx4 v[50:51], v[32:35], off offset:256
	s_waitcnt vmcnt(13)
	s_nop 1
	v_mov_b32_e32 v32, v226
	v_mov_b32_e32 v33, v227
	v_mov_b32_e32 v34, v228
	v_mov_b32_e32 v35, v229
	v_mov_b32_e32 v36, v33
	v_mov_b32_e32 v37, v34
	v_mov_b32_e32 v33, v35
	v_pk_add_f32 v[32:33], v[36:37], v[32:33]
	v_lshlrev_b64 v[34:35], 13, v[48:49]
	v_add_f32_e32 v32, v32, v33
	ds_bpermute_b32 v33, v159, v32
	v_lshl_add_u64 v[34:35], s[10:11], 0, v[34:35]
	v_lshl_add_u64 v[34:35], v[34:35], 0, v[146:147]
	s_waitcnt lgkmcnt(0)
	v_add_f32_e32 v36, v32, v33
	ds_bpermute_b32 v37, v160, v36
	v_add_u32_e32 v32, 0xb0, v148
	v_ashrrev_i32_e32 v33, 31, v32
	s_waitcnt lgkmcnt(0)
	v_add_f32_e32 v36, v36, v37
	v_fmamk_f32 v36, v36, 0x3a800000, v157
	v_mul_f32_e32 v37, 0x4f800000, v36
	v_cmp_gt_f32_e32 vcc, s46, v36
	s_nop 1
	v_cndmask_b32_e32 v38, v36, v37, vcc
	v_sqrt_f32_e32 v39, v38
	v_lshlrev_b64 v[36:37], 6, v[32:33]
	v_lshl_add_u64 v[36:37], v[136:137], 0, v[36:37]
	v_add_u32_e32 v40, -1, v39
	v_add_u32_e32 v41, 1, v39
	v_fma_f32 v42, -v40, v39, v38
	v_fma_f32 v43, -v41, v39, v38
	v_cmp_ge_f32_e64 s[4:5], 0, v42
	s_nop 1
	v_cndmask_b32_e64 v39, v39, v40, s[4:5]
	v_cmp_lt_f32_e64 s[4:5], 0, v43
	s_nop 1
	v_cndmask_b32_e64 v39, v39, v41, s[4:5]
	v_mul_f32_e32 v40, 0x37800000, v39
	v_cndmask_b32_e32 v39, v39, v40, vcc
	v_cmp_class_f32_e32 vcc, v38, v158
	s_nop 1
	v_cndmask_b32_e32 v38, v39, v38, vcc
	v_div_scale_f32 v39, s[4:5], v38, v38, 1.0
	v_rcp_f32_e32 v40, v39
	v_div_scale_f32 v41, vcc, 1.0, v38, 1.0
	v_fma_f32 v42, -v39, v40, 1.0
	v_fmac_f32_e32 v40, v42, v40
	v_mul_f32_e32 v42, v41, v40
	v_fma_f32 v43, -v39, v42, v41
	v_fmac_f32_e32 v42, v43, v40
	v_fma_f32 v39, -v39, v42, v41
	v_div_fmas_f32 v39, v39, v40, v42
	v_div_fixup_f32 v38, v39, v38, 1.0
	v_pk_mul_f32 v[30:31], v[30:31], v[38:39] op_sel_hi:[1,0]
	v_pk_mul_f32 v[28:29], v[28:29], v[38:39] op_sel_hi:[1,0]
	v_pk_mul_f32 v[26:27], v[26:27], v[38:39] op_sel_hi:[1,0]
	v_pk_mul_f32 v[24:25], v[24:25], v[38:39] op_sel_hi:[1,0]
	v_pk_mul_f32 v[18:19], v[18:19], v[38:39] op_sel_hi:[1,0]
	v_pk_mul_f32 v[16:17], v[16:17], v[38:39] op_sel_hi:[1,0]
	v_pk_mul_f32 v[22:23], v[22:23], v[38:39] op_sel_hi:[1,0]
	v_pk_mul_f32 v[20:21], v[20:21], v[38:39] op_sel_hi:[1,0]
	v_max_f32_e32 v28, 0, v28
	v_max_f32_e32 v24, 0, v24
	v_max_f32_e32 v29, 0, v29
	v_max_f32_e32 v25, 0, v25
	v_max_f32_e32 v30, 0, v30
	v_max_f32_e32 v26, 0, v26
	v_max_f32_e32 v31, 0, v31
	v_max_f32_e32 v27, 0, v27
	v_max_f32_e32 v16, 0, v16
	v_max_f32_e32 v17, 0, v17
	v_max_f32_e32 v18, 0, v18
	v_max_f32_e32 v19, 0, v19
	v_max_f32_e32 v20, 0, v20
	v_max_f32_e32 v21, 0, v21
	v_max_f32_e32 v22, 0, v22
	v_max_f32_e32 v23, 0, v23
	v_mul_f32_e32 v28, v28, v28
	v_mul_f32_e32 v24, v24, v24
	v_mul_f32_e32 v29, v29, v29
	v_mul_f32_e32 v25, v25, v25
	v_mul_f32_e32 v30, v30, v30
	v_mul_f32_e32 v26, v26, v26
	v_mul_f32_e32 v31, v31, v31
	v_mul_f32_e32 v27, v27, v27
	v_mul_f32_e32 v38, v16, v16
	v_mul_f32_e32 v39, v17, v17
	v_mul_f32_e32 v40, v18, v18
	v_mul_f32_e32 v41, v19, v19
	v_cvt_pk_bf16_f32 v16, v28, v29
	v_cvt_pk_bf16_f32 v17, v30, v31
	v_cvt_pk_bf16_f32 v18, v24, v25
	v_cvt_pk_bf16_f32 v19, v26, v27
	v_mul_f32_e32 v20, v20, v20
	v_mul_f32_e32 v21, v21, v21
	v_mul_f32_e32 v22, v22, v22
	v_mul_f32_e32 v23, v23, v23
	global_store_dwordx4 v[34:35], v[16:19], off
	s_nop 1
	v_cvt_pk_bf16_f32 v16, v20, v21
	v_cvt_pk_bf16_f32 v17, v22, v23
	v_cvt_pk_bf16_f32 v18, v38, v39
	v_cvt_pk_bf16_f32 v19, v40, v41
	global_store_dwordx4 v[34:35], v[16:19], off offset:256
	s_waitcnt vmcnt(14)
	s_nop 1
	v_mov_b32_e32 v16, v230
	v_mov_b32_e32 v17, v231
	v_mov_b32_e32 v18, v232
	v_mov_b32_e32 v19, v233
	v_mov_b32_e32 v20, v17
	v_mov_b32_e32 v21, v18
	v_mov_b32_e32 v17, v19
	v_pk_add_f32 v[16:17], v[20:21], v[16:17]
	s_nop 0
	v_add_f32_e32 v16, v16, v17
	ds_bpermute_b32 v17, v159, v16
	s_waitcnt lgkmcnt(0)
	v_add_f32_e32 v16, v16, v17
	ds_bpermute_b32 v17, v160, v16
	s_waitcnt lgkmcnt(0)
	v_add_f32_e32 v16, v16, v17
	v_fmamk_f32 v16, v16, 0x3a800000, v157
	v_mul_f32_e32 v17, 0x4f800000, v16
	v_cmp_gt_f32_e32 vcc, s46, v16
	s_nop 1
	v_cndmask_b32_e32 v18, v16, v17, vcc
	v_sqrt_f32_e32 v19, v18
	v_lshlrev_b64 v[16:17], 13, v[32:33]
	v_lshl_add_u64 v[16:17], s[10:11], 0, v[16:17]
	v_lshl_add_u64 v[16:17], v[16:17], 0, v[146:147]
	v_add_u32_e32 v20, -1, v19
	v_add_u32_e32 v21, 1, v19
	v_fma_f32 v22, -v20, v19, v18
	v_fma_f32 v23, -v21, v19, v18
	v_cmp_ge_f32_e64 s[4:5], 0, v22
	s_nop 1
	v_cndmask_b32_e64 v19, v19, v20, s[4:5]
	v_cmp_lt_f32_e64 s[4:5], 0, v23
	s_nop 1
	v_cndmask_b32_e64 v19, v19, v21, s[4:5]
	v_mul_f32_e32 v20, 0x37800000, v19
	v_cndmask_b32_e32 v19, v19, v20, vcc
	v_cmp_class_f32_e32 vcc, v18, v158
	s_nop 1
	v_cndmask_b32_e32 v18, v19, v18, vcc
	v_div_scale_f32 v19, s[4:5], v18, v18, 1.0
	v_rcp_f32_e32 v20, v19
	v_div_scale_f32 v21, vcc, 1.0, v18, 1.0
	v_fma_f32 v22, -v19, v20, 1.0
	v_fmac_f32_e32 v20, v22, v20
	v_mul_f32_e32 v22, v21, v20
	v_fma_f32 v23, -v19, v22, v21
	v_fmac_f32_e32 v22, v23, v20
	v_fma_f32 v19, -v19, v22, v21
	v_div_fmas_f32 v19, v19, v20, v22
	v_div_fixup_f32 v18, v19, v18, 1.0
	v_pk_mul_f32 v[14:15], v[14:15], v[18:19] op_sel_hi:[1,0]
	v_pk_mul_f32 v[12:13], v[12:13], v[18:19] op_sel_hi:[1,0]
	v_pk_mul_f32 v[10:11], v[10:11], v[18:19] op_sel_hi:[1,0]
	v_pk_mul_f32 v[8:9], v[8:9], v[18:19] op_sel_hi:[1,0]
	v_pk_mul_f32 v[2:3], v[2:3], v[18:19] op_sel_hi:[1,0]
	v_pk_mul_f32 v[0:1], v[0:1], v[18:19] op_sel_hi:[1,0]
	v_pk_mul_f32 v[6:7], v[6:7], v[18:19] op_sel_hi:[1,0]
	v_pk_mul_f32 v[4:5], v[4:5], v[18:19] op_sel_hi:[1,0]
	v_max_f32_e32 v12, 0, v12
	v_max_f32_e32 v8, 0, v8
	v_max_f32_e32 v13, 0, v13
	v_max_f32_e32 v9, 0, v9
	v_max_f32_e32 v14, 0, v14
	v_max_f32_e32 v10, 0, v10
	v_max_f32_e32 v15, 0, v15
	v_max_f32_e32 v11, 0, v11
	v_max_f32_e32 v0, 0, v0
	v_max_f32_e32 v1, 0, v1
	v_max_f32_e32 v2, 0, v2
	v_max_f32_e32 v3, 0, v3
	s_andn2_b64 vcc, exec, s[0:1]
	v_max_f32_e32 v4, 0, v4
	v_max_f32_e32 v5, 0, v5
	v_max_f32_e32 v6, 0, v6
	v_max_f32_e32 v7, 0, v7
	v_mul_f32_e32 v12, v12, v12
	v_mul_f32_e32 v8, v8, v8
	v_mul_f32_e32 v13, v13, v13
	v_mul_f32_e32 v9, v9, v9
	v_mul_f32_e32 v14, v14, v14
	v_mul_f32_e32 v10, v10, v10
	v_mul_f32_e32 v15, v15, v15
	v_mul_f32_e32 v11, v11, v11
	v_mul_f32_e32 v18, v0, v0
	v_mul_f32_e32 v19, v1, v1
	v_mul_f32_e32 v20, v2, v2
	v_mul_f32_e32 v21, v3, v3
	v_cvt_pk_bf16_f32 v0, v12, v13
	v_cvt_pk_bf16_f32 v1, v14, v15
	v_cvt_pk_bf16_f32 v2, v8, v9
	v_cvt_pk_bf16_f32 v3, v10, v11
	s_mov_b64 s[0:1], -1
	v_mul_f32_e32 v4, v4, v4
	v_mul_f32_e32 v5, v5, v5
	v_mul_f32_e32 v6, v6, v6
	v_mul_f32_e32 v7, v7, v7
	global_store_dwordx4 v[16:17], v[0:3], off
	s_nop 1
	v_cvt_pk_bf16_f32 v0, v4, v5
	v_cvt_pk_bf16_f32 v1, v6, v7
	v_cvt_pk_bf16_f32 v2, v18, v19
	v_cvt_pk_bf16_f32 v3, v20, v21
	global_store_dwordx4 v[16:17], v[0:3], off offset:256
	s_cbranch_vccnz .LBB0_768
	s_andn2_b64 vcc, exec, s[8:9]
	s_cbranch_vccnz .LBB0_767
	s_barrier
	s_branch .LBB0_767

.LBB0_1252:
	v_lshl_add_u32 v148, s4, 8, v150
	v_ashrrev_i32_e32 v149, 31, v148
	v_lshlrev_b64 v[146:147], 6, v[148:149]
	v_lshl_add_u64 v[146:147], v[136:137], 0, v[146:147]
	s_mov_b64 s[98:99], 0x2000
	global_load_dwordx4 v[160:163], v[146:147], off
	global_load_dwordx4 v[206:209], v[146:147], off offset:1024
	global_load_dwordx4 v[210:213], v[146:147], off offset:2048
	global_load_dwordx4 v[214:217], v[146:147], off offset:3072
	v_lshl_add_u64 v[194:195], v[146:147], 0, s[98:99]
	global_load_dwordx4 v[218:221], v[194:195], off
	global_load_dwordx4 v[222:225], v[194:195], off offset:1024
	global_load_dwordx4 v[226:229], v[194:195], off offset:2048
	global_load_dwordx4 v[230:233], v[194:195], off offset:3072
	v_and_b32_e32 v159, 64, v156
	v_xor_b32_e32 v147, 16, v156
	v_add_u32_e32 v167, 64, v159
	v_cmp_lt_i32_e32 vcc, v147, v167
	v_xor_b32_e32 v166, 32, v156
	v_lshl_or_b32 v146, s5, 8, v152
	v_cndmask_b32_e32 v147, v156, v147, vcc
	v_lshlrev_b32_e32 v159, 2, v147
	v_cmp_lt_i32_e32 vcc, v166, v167
	v_ashrrev_i32_e32 v147, 31, v146
	v_lshlrev_b64 v[146:147], 1, v[146:147]
	s_waitcnt vmcnt(7)
	v_mov_b32_e32 v164, v161
	v_mov_b32_e32 v165, v162
	v_mov_b32_e32 v161, v163
	v_pk_add_f32 v[160:161], v[164:165], v[160:161]
	v_lshlrev_b64 v[164:165], 13, v[148:149]
	v_add_f32_e32 v161, v160, v161
	ds_bpermute_b32 v162, v159, v161
	v_cndmask_b32_e32 v160, v156, v166, vcc
	v_lshlrev_b32_e32 v160, 2, v160
	v_lshl_add_u64 v[164:165], s[10:11], 0, v[164:165]
	v_lshl_add_u64 v[164:165], v[164:165], 0, v[146:147]
	s_waitcnt lgkmcnt(0)
	v_add_f32_e32 v161, v161, v162
	ds_bpermute_b32 v166, v160, v161
	v_or_b32_e32 v162, 16, v148
	v_ashrrev_i32_e32 v163, 31, v162
	s_waitcnt lgkmcnt(0)
	v_add_f32_e32 v149, v161, v166
	v_fmamk_f32 v149, v149, 0x3a800000, v157
	v_mul_f32_e32 v161, 0x4f800000, v149
	v_cmp_gt_f32_e32 vcc, s46, v149
	v_lshlrev_b64 v[166:167], 6, v[162:163]
	v_lshl_add_u64 v[166:167], v[136:137], 0, v[166:167]
	v_cndmask_b32_e32 v149, v149, v161, vcc
	v_sqrt_f32_e32 v161, v149
	s_nop 0
	v_add_u32_e32 v168, -1, v161
	v_add_u32_e32 v169, 1, v161
	v_fma_f32 v170, -v168, v161, v149
	v_fma_f32 v171, -v169, v161, v149
	v_cmp_ge_f32_e64 s[4:5], 0, v170
	s_nop 1
	v_cndmask_b32_e64 v161, v161, v168, s[4:5]
	v_cmp_lt_f32_e64 s[4:5], 0, v171
	s_nop 1
	v_cndmask_b32_e64 v161, v161, v169, s[4:5]
	v_mul_f32_e32 v168, 0x37800000, v161
	v_cndmask_b32_e32 v161, v161, v168, vcc
	v_cmp_class_f32_e32 vcc, v149, v158
	s_nop 1
	v_cndmask_b32_e32 v149, v161, v149, vcc
	v_div_scale_f32 v161, s[4:5], v149, v149, 1.0
	v_rcp_f32_e32 v168, v161
	v_div_scale_f32 v169, vcc, 1.0, v149, 1.0
	v_fma_f32 v170, -v161, v168, 1.0
	v_fmac_f32_e32 v168, v170, v168
	v_mul_f32_e32 v170, v169, v168
	v_fma_f32 v171, -v161, v170, v169
	v_fmac_f32_e32 v170, v171, v168
	v_fma_f32 v161, -v161, v170, v169
	v_div_fmas_f32 v161, v161, v168, v170
	v_div_fixup_f32 v168, v161, v149, 1.0
	v_pk_mul_f32 v[126:127], v[126:127], v[168:169] op_sel_hi:[1,0]
	v_pk_mul_f32 v[124:125], v[124:125], v[168:169] op_sel_hi:[1,0]
	v_pk_mul_f32 v[122:123], v[122:123], v[168:169] op_sel_hi:[1,0]
	v_pk_mul_f32 v[120:121], v[120:121], v[168:169] op_sel_hi:[1,0]
	v_pk_mul_f32 v[114:115], v[114:115], v[168:169] op_sel_hi:[1,0]
	v_pk_mul_f32 v[112:113], v[112:113], v[168:169] op_sel_hi:[1,0]
	v_pk_mul_f32 v[118:119], v[118:119], v[168:169] op_sel_hi:[1,0]
	v_pk_mul_f32 v[116:117], v[116:117], v[168:169] op_sel_hi:[1,0]
	v_max_f32_e32 v124, 0, v124
	v_max_f32_e32 v120, 0, v120
	v_max_f32_e32 v125, 0, v125
	v_max_f32_e32 v121, 0, v121
	v_max_f32_e32 v126, 0, v126
	v_max_f32_e32 v122, 0, v122
	v_max_f32_e32 v127, 0, v127
	v_max_f32_e32 v123, 0, v123
	v_max_f32_e32 v112, 0, v112
	v_max_f32_e32 v113, 0, v113
	v_max_f32_e32 v114, 0, v114
	v_max_f32_e32 v115, 0, v115
	v_max_f32_e32 v116, 0, v116
	v_max_f32_e32 v117, 0, v117
	v_max_f32_e32 v118, 0, v118
	v_max_f32_e32 v119, 0, v119
	v_mul_f32_e32 v124, v124, v124
	v_mul_f32_e32 v120, v120, v120
	v_mul_f32_e32 v125, v125, v125
	v_mul_f32_e32 v121, v121, v121
	v_mul_f32_e32 v126, v126, v126
	v_mul_f32_e32 v122, v122, v122
	v_mul_f32_e32 v127, v127, v127
	v_mul_f32_e32 v123, v123, v123
	v_mul_f32_e32 v149, v112, v112
	v_mul_f32_e32 v161, v113, v113
	v_mul_f32_e32 v168, v114, v114
	v_mul_f32_e32 v169, v115, v115
	v_cvt_pk_bf16_f32 v112, v124, v125
	v_cvt_pk_bf16_f32 v113, v126, v127
	v_cvt_pk_bf16_f32 v114, v120, v121
	v_cvt_pk_bf16_f32 v115, v122, v123
	v_mul_f32_e32 v116, v116, v116
	v_mul_f32_e32 v117, v117, v117
	v_mul_f32_e32 v118, v118, v118
	v_mul_f32_e32 v119, v119, v119
	global_store_dwordx4 v[164:165], v[112:115], off
	s_nop 1
	v_cvt_pk_bf16_f32 v112, v116, v117
	v_cvt_pk_bf16_f32 v113, v118, v119
	v_cvt_pk_bf16_f32 v114, v149, v161
	v_cvt_pk_bf16_f32 v115, v168, v169
	global_store_dwordx4 v[164:165], v[112:115], off offset:256
	s_waitcnt vmcnt(8)
	s_nop 1
	v_mov_b32_e32 v112, v206
	v_mov_b32_e32 v113, v207
	v_mov_b32_e32 v114, v208
	v_mov_b32_e32 v115, v209
	v_mov_b32_e32 v116, v113
	v_mov_b32_e32 v117, v114
	v_mov_b32_e32 v113, v115
	v_pk_add_f32 v[112:113], v[116:117], v[112:113]
	v_lshlrev_b64 v[114:115], 13, v[162:163]
	v_add_f32_e32 v112, v112, v113
	ds_bpermute_b32 v113, v159, v112
	v_lshl_add_u64 v[114:115], s[10:11], 0, v[114:115]
	v_lshl_add_u64 v[114:115], v[114:115], 0, v[146:147]
	s_waitcnt lgkmcnt(0)
	v_add_f32_e32 v116, v112, v113
	ds_bpermute_b32 v117, v160, v116
	v_or_b32_e32 v112, 32, v148
	v_ashrrev_i32_e32 v113, 31, v112
	s_waitcnt lgkmcnt(0)
	v_add_f32_e32 v116, v116, v117
	v_fmamk_f32 v116, v116, 0x3a800000, v157
	v_mul_f32_e32 v117, 0x4f800000, v116
	v_cmp_gt_f32_e32 vcc, s46, v116
	s_nop 1
	v_cndmask_b32_e32 v118, v116, v117, vcc
	v_sqrt_f32_e32 v119, v118
	v_lshlrev_b64 v[116:117], 6, v[112:113]
	v_lshl_add_u64 v[116:117], v[136:137], 0, v[116:117]
	v_add_u32_e32 v120, -1, v119
	v_add_u32_e32 v121, 1, v119
	v_fma_f32 v122, -v120, v119, v118
	v_fma_f32 v123, -v121, v119, v118
	v_cmp_ge_f32_e64 s[4:5], 0, v122
	s_nop 1
	v_cndmask_b32_e64 v119, v119, v120, s[4:5]
	v_cmp_lt_f32_e64 s[4:5], 0, v123
	s_nop 1
	v_cndmask_b32_e64 v119, v119, v121, s[4:5]
	v_mul_f32_e32 v120, 0x37800000, v119
	v_cndmask_b32_e32 v119, v119, v120, vcc
	v_cmp_class_f32_e32 vcc, v118, v158
	s_nop 1
	v_cndmask_b32_e32 v118, v119, v118, vcc
	v_div_scale_f32 v119, s[4:5], v118, v118, 1.0
	v_rcp_f32_e32 v120, v119
	v_div_scale_f32 v121, vcc, 1.0, v118, 1.0
	v_fma_f32 v122, -v119, v120, 1.0
	v_fmac_f32_e32 v120, v122, v120
	v_mul_f32_e32 v122, v121, v120
	v_fma_f32 v123, -v119, v122, v121
	v_fmac_f32_e32 v122, v123, v120
	v_fma_f32 v119, -v119, v122, v121
	v_div_fmas_f32 v119, v119, v120, v122
	v_div_fixup_f32 v118, v119, v118, 1.0
	v_pk_mul_f32 v[110:111], v[110:111], v[118:119] op_sel_hi:[1,0]
	v_pk_mul_f32 v[108:109], v[108:109], v[118:119] op_sel_hi:[1,0]
	v_pk_mul_f32 v[106:107], v[106:107], v[118:119] op_sel_hi:[1,0]
	v_pk_mul_f32 v[104:105], v[104:105], v[118:119] op_sel_hi:[1,0]
	v_pk_mul_f32 v[98:99], v[98:99], v[118:119] op_sel_hi:[1,0]
	v_pk_mul_f32 v[96:97], v[96:97], v[118:119] op_sel_hi:[1,0]
	v_pk_mul_f32 v[102:103], v[102:103], v[118:119] op_sel_hi:[1,0]
	v_pk_mul_f32 v[100:101], v[100:101], v[118:119] op_sel_hi:[1,0]
	v_max_f32_e32 v108, 0, v108
	v_max_f32_e32 v104, 0, v104
	v_max_f32_e32 v109, 0, v109
	v_max_f32_e32 v105, 0, v105
	v_max_f32_e32 v110, 0, v110
	v_max_f32_e32 v106, 0, v106
	v_max_f32_e32 v111, 0, v111
	v_max_f32_e32 v107, 0, v107
	v_max_f32_e32 v96, 0, v96
	v_max_f32_e32 v97, 0, v97
	v_max_f32_e32 v98, 0, v98
	v_max_f32_e32 v99, 0, v99
	v_max_f32_e32 v100, 0, v100
	v_max_f32_e32 v101, 0, v101
	v_max_f32_e32 v102, 0, v102
	v_max_f32_e32 v103, 0, v103
	v_mul_f32_e32 v108, v108, v108
	v_mul_f32_e32 v104, v104, v104
	v_mul_f32_e32 v109, v109, v109
	v_mul_f32_e32 v105, v105, v105
	v_mul_f32_e32 v110, v110, v110
	v_mul_f32_e32 v106, v106, v106
	v_mul_f32_e32 v111, v111, v111
	v_mul_f32_e32 v107, v107, v107
	v_mul_f32_e32 v118, v96, v96
	v_mul_f32_e32 v119, v97, v97
	v_mul_f32_e32 v120, v98, v98
	v_mul_f32_e32 v121, v99, v99
	v_cvt_pk_bf16_f32 v96, v108, v109
	v_cvt_pk_bf16_f32 v97, v110, v111
	v_cvt_pk_bf16_f32 v98, v104, v105
	v_cvt_pk_bf16_f32 v99, v106, v107
	v_mul_f32_e32 v100, v100, v100
	v_mul_f32_e32 v101, v101, v101
	v_mul_f32_e32 v102, v102, v102
	v_mul_f32_e32 v103, v103, v103
	global_store_dwordx4 v[114:115], v[96:99], off
	s_nop 1
	v_cvt_pk_bf16_f32 v96, v100, v101
	v_cvt_pk_bf16_f32 v97, v102, v103
	v_cvt_pk_bf16_f32 v98, v118, v119
	v_cvt_pk_bf16_f32 v99, v120, v121
	global_store_dwordx4 v[114:115], v[96:99], off offset:256
	s_waitcnt vmcnt(9)
	s_nop 1
	v_mov_b32_e32 v96, v210
	v_mov_b32_e32 v97, v211
	v_mov_b32_e32 v98, v212
	v_mov_b32_e32 v99, v213
	v_mov_b32_e32 v100, v97
	v_mov_b32_e32 v101, v98
	v_mov_b32_e32 v97, v99
	v_pk_add_f32 v[96:97], v[100:101], v[96:97]
	v_lshlrev_b64 v[98:99], 13, v[112:113]
	v_add_f32_e32 v96, v96, v97
	ds_bpermute_b32 v97, v159, v96
	v_lshl_add_u64 v[98:99], s[10:11], 0, v[98:99]
	v_lshl_add_u64 v[98:99], v[98:99], 0, v[146:147]
	s_waitcnt lgkmcnt(0)
	v_add_f32_e32 v100, v96, v97
	ds_bpermute_b32 v101, v160, v100
	v_or_b32_e32 v96, 48, v148
	v_ashrrev_i32_e32 v97, 31, v96
	s_waitcnt lgkmcnt(0)
	v_add_f32_e32 v100, v100, v101
	v_fmamk_f32 v100, v100, 0x3a800000, v157
	v_mul_f32_e32 v101, 0x4f800000, v100
	v_cmp_gt_f32_e32 vcc, s46, v100
	s_nop 1
	v_cndmask_b32_e32 v102, v100, v101, vcc
	v_sqrt_f32_e32 v103, v102
	v_lshlrev_b64 v[100:101], 6, v[96:97]
	v_lshl_add_u64 v[100:101], v[136:137], 0, v[100:101]
	v_add_u32_e32 v104, -1, v103
	v_add_u32_e32 v105, 1, v103
	v_fma_f32 v106, -v104, v103, v102
	v_fma_f32 v107, -v105, v103, v102
	v_cmp_ge_f32_e64 s[4:5], 0, v106
	s_nop 1
	v_cndmask_b32_e64 v103, v103, v104, s[4:5]
	v_cmp_lt_f32_e64 s[4:5], 0, v107
	s_nop 1
	v_cndmask_b32_e64 v103, v103, v105, s[4:5]
	v_mul_f32_e32 v104, 0x37800000, v103
	v_cndmask_b32_e32 v103, v103, v104, vcc
	v_cmp_class_f32_e32 vcc, v102, v158
	s_nop 1
	v_cndmask_b32_e32 v102, v103, v102, vcc
	v_div_scale_f32 v103, s[4:5], v102, v102, 1.0
	v_rcp_f32_e32 v104, v103
	v_div_scale_f32 v105, vcc, 1.0, v102, 1.0
	v_fma_f32 v106, -v103, v104, 1.0
	v_fmac_f32_e32 v104, v106, v104
	v_mul_f32_e32 v106, v105, v104
	v_fma_f32 v107, -v103, v106, v105
	v_fmac_f32_e32 v106, v107, v104
	v_fma_f32 v103, -v103, v106, v105
	v_div_fmas_f32 v103, v103, v104, v106
	v_div_fixup_f32 v102, v103, v102, 1.0
	v_pk_mul_f32 v[94:95], v[94:95], v[102:103] op_sel_hi:[1,0]
	v_pk_mul_f32 v[92:93], v[92:93], v[102:103] op_sel_hi:[1,0]
	v_pk_mul_f32 v[90:91], v[90:91], v[102:103] op_sel_hi:[1,0]
	v_pk_mul_f32 v[88:89], v[88:89], v[102:103] op_sel_hi:[1,0]
	v_pk_mul_f32 v[82:83], v[82:83], v[102:103] op_sel_hi:[1,0]
	v_pk_mul_f32 v[80:81], v[80:81], v[102:103] op_sel_hi:[1,0]
	v_pk_mul_f32 v[86:87], v[86:87], v[102:103] op_sel_hi:[1,0]
	v_pk_mul_f32 v[84:85], v[84:85], v[102:103] op_sel_hi:[1,0]
	v_max_f32_e32 v92, 0, v92
	v_max_f32_e32 v88, 0, v88
	v_max_f32_e32 v93, 0, v93
	v_max_f32_e32 v89, 0, v89
	v_max_f32_e32 v94, 0, v94
	v_max_f32_e32 v90, 0, v90
	v_max_f32_e32 v95, 0, v95
	v_max_f32_e32 v91, 0, v91
	v_max_f32_e32 v80, 0, v80
	v_max_f32_e32 v81, 0, v81
	v_max_f32_e32 v82, 0, v82
	v_max_f32_e32 v83, 0, v83
	v_max_f32_e32 v84, 0, v84
	v_max_f32_e32 v85, 0, v85
	v_max_f32_e32 v86, 0, v86
	v_max_f32_e32 v87, 0, v87
	v_mul_f32_e32 v92, v92, v92
	v_mul_f32_e32 v88, v88, v88
	v_mul_f32_e32 v93, v93, v93
	v_mul_f32_e32 v89, v89, v89
	v_mul_f32_e32 v94, v94, v94
	v_mul_f32_e32 v90, v90, v90
	v_mul_f32_e32 v95, v95, v95
	v_mul_f32_e32 v91, v91, v91
	v_mul_f32_e32 v102, v80, v80
	v_mul_f32_e32 v103, v81, v81
	v_mul_f32_e32 v104, v82, v82
	v_mul_f32_e32 v105, v83, v83
	v_cvt_pk_bf16_f32 v80, v92, v93
	v_cvt_pk_bf16_f32 v81, v94, v95
	v_cvt_pk_bf16_f32 v82, v88, v89
	v_cvt_pk_bf16_f32 v83, v90, v91
	v_mul_f32_e32 v84, v84, v84
	v_mul_f32_e32 v85, v85, v85
	v_mul_f32_e32 v86, v86, v86
	v_mul_f32_e32 v87, v87, v87
	global_store_dwordx4 v[98:99], v[80:83], off
	s_nop 1
	v_cvt_pk_bf16_f32 v80, v84, v85
	v_cvt_pk_bf16_f32 v81, v86, v87
	v_cvt_pk_bf16_f32 v82, v102, v103
	v_cvt_pk_bf16_f32 v83, v104, v105
	global_store_dwordx4 v[98:99], v[80:83], off offset:256
	s_waitcnt vmcnt(10)
	s_nop 1
	v_mov_b32_e32 v80, v214
	v_mov_b32_e32 v81, v215
	v_mov_b32_e32 v82, v216
	v_mov_b32_e32 v83, v217
	v_mov_b32_e32 v84, v81
	v_mov_b32_e32 v85, v82
	v_mov_b32_e32 v81, v83
	v_pk_add_f32 v[80:81], v[84:85], v[80:81]
	v_lshlrev_b64 v[82:83], 13, v[96:97]
	v_add_f32_e32 v80, v80, v81
	ds_bpermute_b32 v81, v159, v80
	v_lshl_add_u64 v[82:83], s[10:11], 0, v[82:83]
	v_lshl_add_u64 v[82:83], v[82:83], 0, v[146:147]
	s_waitcnt lgkmcnt(0)
	v_add_f32_e32 v84, v80, v81
	ds_bpermute_b32 v85, v160, v84
	v_add_u32_e32 v80, 0x80, v148
	v_ashrrev_i32_e32 v81, 31, v80
	s_waitcnt lgkmcnt(0)
	v_add_f32_e32 v84, v84, v85
	v_fmamk_f32 v84, v84, 0x3a800000, v157
	v_mul_f32_e32 v85, 0x4f800000, v84
	v_cmp_gt_f32_e32 vcc, s46, v84
	s_nop 1
	v_cndmask_b32_e32 v86, v84, v85, vcc
	v_sqrt_f32_e32 v87, v86
	v_lshlrev_b64 v[84:85], 6, v[80:81]
	v_lshl_add_u64 v[84:85], v[136:137], 0, v[84:85]
	v_add_u32_e32 v88, -1, v87
	v_add_u32_e32 v89, 1, v87
	v_fma_f32 v90, -v88, v87, v86
	v_fma_f32 v91, -v89, v87, v86
	v_cmp_ge_f32_e64 s[4:5], 0, v90
	s_nop 1
	v_cndmask_b32_e64 v87, v87, v88, s[4:5]
	v_cmp_lt_f32_e64 s[4:5], 0, v91
	s_nop 1
	v_cndmask_b32_e64 v87, v87, v89, s[4:5]
	v_mul_f32_e32 v88, 0x37800000, v87
	v_cndmask_b32_e32 v87, v87, v88, vcc
	v_cmp_class_f32_e32 vcc, v86, v158
	s_nop 1
	v_cndmask_b32_e32 v86, v87, v86, vcc
	v_div_scale_f32 v87, s[4:5], v86, v86, 1.0
	v_rcp_f32_e32 v88, v87
	v_div_scale_f32 v89, vcc, 1.0, v86, 1.0
	v_fma_f32 v90, -v87, v88, 1.0
	v_fmac_f32_e32 v88, v90, v88
	v_mul_f32_e32 v90, v89, v88
	v_fma_f32 v91, -v87, v90, v89
	v_fmac_f32_e32 v90, v91, v88
	v_fma_f32 v87, -v87, v90, v89
	v_div_fmas_f32 v87, v87, v88, v90
	v_div_fixup_f32 v86, v87, v86, 1.0
	v_pk_mul_f32 v[78:79], v[78:79], v[86:87] op_sel_hi:[1,0]
	v_pk_mul_f32 v[76:77], v[76:77], v[86:87] op_sel_hi:[1,0]
	v_pk_mul_f32 v[74:75], v[74:75], v[86:87] op_sel_hi:[1,0]
	v_pk_mul_f32 v[72:73], v[72:73], v[86:87] op_sel_hi:[1,0]
	v_pk_mul_f32 v[66:67], v[66:67], v[86:87] op_sel_hi:[1,0]
	v_pk_mul_f32 v[64:65], v[64:65], v[86:87] op_sel_hi:[1,0]
	v_pk_mul_f32 v[70:71], v[70:71], v[86:87] op_sel_hi:[1,0]
	v_pk_mul_f32 v[68:69], v[68:69], v[86:87] op_sel_hi:[1,0]
	v_max_f32_e32 v76, 0, v76
	v_max_f32_e32 v72, 0, v72
	v_max_f32_e32 v77, 0, v77
	v_max_f32_e32 v73, 0, v73
	v_max_f32_e32 v78, 0, v78
	v_max_f32_e32 v74, 0, v74
	v_max_f32_e32 v79, 0, v79
	v_max_f32_e32 v75, 0, v75
	v_max_f32_e32 v64, 0, v64
	v_max_f32_e32 v65, 0, v65
	v_max_f32_e32 v66, 0, v66
	v_max_f32_e32 v67, 0, v67
	v_max_f32_e32 v68, 0, v68
	v_max_f32_e32 v69, 0, v69
	v_max_f32_e32 v70, 0, v70
	v_max_f32_e32 v71, 0, v71
	v_mul_f32_e32 v76, v76, v76
	v_mul_f32_e32 v72, v72, v72
	v_mul_f32_e32 v77, v77, v77
	v_mul_f32_e32 v73, v73, v73
	v_mul_f32_e32 v78, v78, v78
	v_mul_f32_e32 v74, v74, v74
	v_mul_f32_e32 v79, v79, v79
	v_mul_f32_e32 v75, v75, v75
	v_mul_f32_e32 v86, v64, v64
	v_mul_f32_e32 v87, v65, v65
	v_mul_f32_e32 v88, v66, v66
	v_mul_f32_e32 v89, v67, v67
	v_cvt_pk_bf16_f32 v64, v76, v77
	v_cvt_pk_bf16_f32 v65, v78, v79
	v_cvt_pk_bf16_f32 v66, v72, v73
	v_cvt_pk_bf16_f32 v67, v74, v75
	v_mul_f32_e32 v68, v68, v68
	v_mul_f32_e32 v69, v69, v69
	v_mul_f32_e32 v70, v70, v70
	v_mul_f32_e32 v71, v71, v71
	global_store_dwordx4 v[82:83], v[64:67], off
	s_nop 1
	v_cvt_pk_bf16_f32 v64, v68, v69
	v_cvt_pk_bf16_f32 v65, v70, v71
	v_cvt_pk_bf16_f32 v66, v86, v87
	v_cvt_pk_bf16_f32 v67, v88, v89
	global_store_dwordx4 v[82:83], v[64:67], off offset:256
	s_waitcnt vmcnt(11)
	s_nop 1
	v_mov_b32_e32 v64, v218
	v_mov_b32_e32 v65, v219
	v_mov_b32_e32 v66, v220
	v_mov_b32_e32 v67, v221
	v_mov_b32_e32 v68, v65
	v_mov_b32_e32 v69, v66
	v_mov_b32_e32 v65, v67
	v_pk_add_f32 v[64:65], v[68:69], v[64:65]
	v_lshlrev_b64 v[66:67], 13, v[80:81]
	v_add_f32_e32 v64, v64, v65
	ds_bpermute_b32 v65, v159, v64
	v_lshl_add_u64 v[66:67], s[10:11], 0, v[66:67]
	v_lshl_add_u64 v[66:67], v[66:67], 0, v[146:147]
	s_waitcnt lgkmcnt(0)
	v_add_f32_e32 v68, v64, v65
	ds_bpermute_b32 v69, v160, v68
	v_add_u32_e32 v64, 0x90, v148
	v_ashrrev_i32_e32 v65, 31, v64
	s_waitcnt lgkmcnt(0)
	v_add_f32_e32 v68, v68, v69
	v_fmamk_f32 v68, v68, 0x3a800000, v157
	v_mul_f32_e32 v69, 0x4f800000, v68
	v_cmp_gt_f32_e32 vcc, s46, v68
	s_nop 1
	v_cndmask_b32_e32 v70, v68, v69, vcc
	v_sqrt_f32_e32 v71, v70
	v_lshlrev_b64 v[68:69], 6, v[64:65]
	v_lshl_add_u64 v[68:69], v[136:137], 0, v[68:69]
	v_add_u32_e32 v72, -1, v71
	v_add_u32_e32 v73, 1, v71
	v_fma_f32 v74, -v72, v71, v70
	v_fma_f32 v75, -v73, v71, v70
	v_cmp_ge_f32_e64 s[4:5], 0, v74
	s_nop 1
	v_cndmask_b32_e64 v71, v71, v72, s[4:5]
	v_cmp_lt_f32_e64 s[4:5], 0, v75
	s_nop 1
	v_cndmask_b32_e64 v71, v71, v73, s[4:5]
	v_mul_f32_e32 v72, 0x37800000, v71
	v_cndmask_b32_e32 v71, v71, v72, vcc
	v_cmp_class_f32_e32 vcc, v70, v158
	s_nop 1
	v_cndmask_b32_e32 v70, v71, v70, vcc
	v_div_scale_f32 v71, s[4:5], v70, v70, 1.0
	v_rcp_f32_e32 v72, v71
	v_div_scale_f32 v73, vcc, 1.0, v70, 1.0
	v_fma_f32 v74, -v71, v72, 1.0
	v_fmac_f32_e32 v72, v74, v72
	v_mul_f32_e32 v74, v73, v72
	v_fma_f32 v75, -v71, v74, v73
	v_fmac_f32_e32 v74, v75, v72
	v_fma_f32 v71, -v71, v74, v73
	v_div_fmas_f32 v71, v71, v72, v74
	v_div_fixup_f32 v70, v71, v70, 1.0
	v_pk_mul_f32 v[62:63], v[62:63], v[70:71] op_sel_hi:[1,0]
	v_pk_mul_f32 v[60:61], v[60:61], v[70:71] op_sel_hi:[1,0]
	v_pk_mul_f32 v[58:59], v[58:59], v[70:71] op_sel_hi:[1,0]
	v_pk_mul_f32 v[56:57], v[56:57], v[70:71] op_sel_hi:[1,0]
	v_pk_mul_f32 v[50:51], v[50:51], v[70:71] op_sel_hi:[1,0]
	v_pk_mul_f32 v[48:49], v[48:49], v[70:71] op_sel_hi:[1,0]
	v_pk_mul_f32 v[54:55], v[54:55], v[70:71] op_sel_hi:[1,0]
	v_pk_mul_f32 v[52:53], v[52:53], v[70:71] op_sel_hi:[1,0]
	v_max_f32_e32 v60, 0, v60
	v_max_f32_e32 v56, 0, v56
	v_max_f32_e32 v61, 0, v61
	v_max_f32_e32 v57, 0, v57
	v_max_f32_e32 v62, 0, v62
	v_max_f32_e32 v58, 0, v58
	v_max_f32_e32 v63, 0, v63
	v_max_f32_e32 v59, 0, v59
	v_max_f32_e32 v48, 0, v48
	v_max_f32_e32 v49, 0, v49
	v_max_f32_e32 v50, 0, v50
	v_max_f32_e32 v51, 0, v51
	v_max_f32_e32 v52, 0, v52
	v_max_f32_e32 v53, 0, v53
	v_max_f32_e32 v54, 0, v54
	v_max_f32_e32 v55, 0, v55
	v_mul_f32_e32 v60, v60, v60
	v_mul_f32_e32 v56, v56, v56
	v_mul_f32_e32 v61, v61, v61
	v_mul_f32_e32 v57, v57, v57
	v_mul_f32_e32 v62, v62, v62
	v_mul_f32_e32 v58, v58, v58
	v_mul_f32_e32 v63, v63, v63
	v_mul_f32_e32 v59, v59, v59
	v_mul_f32_e32 v70, v48, v48
	v_mul_f32_e32 v71, v49, v49
	v_mul_f32_e32 v72, v50, v50
	v_mul_f32_e32 v73, v51, v51
	v_cvt_pk_bf16_f32 v48, v60, v61
	v_cvt_pk_bf16_f32 v49, v62, v63
	v_cvt_pk_bf16_f32 v50, v56, v57
	v_cvt_pk_bf16_f32 v51, v58, v59
	v_mul_f32_e32 v52, v52, v52
	v_mul_f32_e32 v53, v53, v53
	v_mul_f32_e32 v54, v54, v54
	v_mul_f32_e32 v55, v55, v55
	global_store_dwordx4 v[66:67], v[48:51], off
	s_nop 1
	v_cvt_pk_bf16_f32 v48, v52, v53
	v_cvt_pk_bf16_f32 v49, v54, v55
	v_cvt_pk_bf16_f32 v50, v70, v71
	v_cvt_pk_bf16_f32 v51, v72, v73
	global_store_dwordx4 v[66:67], v[48:51], off offset:256
	s_waitcnt vmcnt(12)
	s_nop 1
	v_mov_b32_e32 v48, v222
	v_mov_b32_e32 v49, v223
	v_mov_b32_e32 v50, v224
	v_mov_b32_e32 v51, v225
	v_mov_b32_e32 v52, v49
	v_mov_b32_e32 v53, v50
	v_mov_b32_e32 v49, v51
	v_pk_add_f32 v[48:49], v[52:53], v[48:49]
	v_lshlrev_b64 v[50:51], 13, v[64:65]
	v_add_f32_e32 v48, v48, v49
	ds_bpermute_b32 v49, v159, v48
	v_lshl_add_u64 v[50:51], s[10:11], 0, v[50:51]
	v_lshl_add_u64 v[50:51], v[50:51], 0, v[146:147]
	s_waitcnt lgkmcnt(0)
	v_add_f32_e32 v52, v48, v49
	ds_bpermute_b32 v53, v160, v52
	v_add_u32_e32 v48, 0xa0, v148
	v_ashrrev_i32_e32 v49, 31, v48
	s_waitcnt lgkmcnt(0)
	v_add_f32_e32 v52, v52, v53
	v_fmamk_f32 v52, v52, 0x3a800000, v157
	v_mul_f32_e32 v53, 0x4f800000, v52
	v_cmp_gt_f32_e32 vcc, s46, v52
	s_nop 1
	v_cndmask_b32_e32 v54, v52, v53, vcc
	v_sqrt_f32_e32 v55, v54
	v_lshlrev_b64 v[52:53], 6, v[48:49]
	v_lshl_add_u64 v[52:53], v[136:137], 0, v[52:53]
	v_add_u32_e32 v56, -1, v55
	v_add_u32_e32 v57, 1, v55
	v_fma_f32 v58, -v56, v55, v54
	v_fma_f32 v59, -v57, v55, v54
	v_cmp_ge_f32_e64 s[4:5], 0, v58
	s_nop 1
	v_cndmask_b32_e64 v55, v55, v56, s[4:5]
	v_cmp_lt_f32_e64 s[4:5], 0, v59
	s_nop 1
	v_cndmask_b32_e64 v55, v55, v57, s[4:5]
	v_mul_f32_e32 v56, 0x37800000, v55
	v_cndmask_b32_e32 v55, v55, v56, vcc
	v_cmp_class_f32_e32 vcc, v54, v158
	s_nop 1
	v_cndmask_b32_e32 v54, v55, v54, vcc
	v_div_scale_f32 v55, s[4:5], v54, v54, 1.0
	v_rcp_f32_e32 v56, v55
	v_div_scale_f32 v57, vcc, 1.0, v54, 1.0
	v_fma_f32 v58, -v55, v56, 1.0
	v_fmac_f32_e32 v56, v58, v56
	v_mul_f32_e32 v58, v57, v56
	v_fma_f32 v59, -v55, v58, v57
	v_fmac_f32_e32 v58, v59, v56
	v_fma_f32 v55, -v55, v58, v57
	v_div_fmas_f32 v55, v55, v56, v58
	v_div_fixup_f32 v54, v55, v54, 1.0
	v_pk_mul_f32 v[46:47], v[46:47], v[54:55] op_sel_hi:[1,0]
	v_pk_mul_f32 v[44:45], v[44:45], v[54:55] op_sel_hi:[1,0]
	v_pk_mul_f32 v[42:43], v[42:43], v[54:55] op_sel_hi:[1,0]
	v_pk_mul_f32 v[40:41], v[40:41], v[54:55] op_sel_hi:[1,0]
	v_pk_mul_f32 v[34:35], v[34:35], v[54:55] op_sel_hi:[1,0]
	v_pk_mul_f32 v[32:33], v[32:33], v[54:55] op_sel_hi:[1,0]
	v_pk_mul_f32 v[38:39], v[38:39], v[54:55] op_sel_hi:[1,0]
	v_pk_mul_f32 v[36:37], v[36:37], v[54:55] op_sel_hi:[1,0]
	v_max_f32_e32 v44, 0, v44
	v_max_f32_e32 v40, 0, v40
	v_max_f32_e32 v45, 0, v45
	v_max_f32_e32 v41, 0, v41
	v_max_f32_e32 v46, 0, v46
	v_max_f32_e32 v42, 0, v42
	v_max_f32_e32 v47, 0, v47
	v_max_f32_e32 v43, 0, v43
	v_max_f32_e32 v32, 0, v32
	v_max_f32_e32 v33, 0, v33
	v_max_f32_e32 v34, 0, v34
	v_max_f32_e32 v35, 0, v35
	v_max_f32_e32 v36, 0, v36
	v_max_f32_e32 v37, 0, v37
	v_max_f32_e32 v38, 0, v38
	v_max_f32_e32 v39, 0, v39
	v_mul_f32_e32 v44, v44, v44
	v_mul_f32_e32 v40, v40, v40
	v_mul_f32_e32 v45, v45, v45
	v_mul_f32_e32 v41, v41, v41
	v_mul_f32_e32 v46, v46, v46
	v_mul_f32_e32 v42, v42, v42
	v_mul_f32_e32 v47, v47, v47
	v_mul_f32_e32 v43, v43, v43
	v_mul_f32_e32 v54, v32, v32
	v_mul_f32_e32 v55, v33, v33
	v_mul_f32_e32 v56, v34, v34
	v_mul_f32_e32 v57, v35, v35
	v_cvt_pk_bf16_f32 v32, v44, v45
	v_cvt_pk_bf16_f32 v33, v46, v47
	v_cvt_pk_bf16_f32 v34, v40, v41
	v_cvt_pk_bf16_f32 v35, v42, v43
	v_mul_f32_e32 v36, v36, v36
	v_mul_f32_e32 v37, v37, v37
	v_mul_f32_e32 v38, v38, v38
	v_mul_f32_e32 v39, v39, v39
	global_store_dwordx4 v[50:51], v[32:35], off
	s_nop 1
	v_cvt_pk_bf16_f32 v32, v36, v37
	v_cvt_pk_bf16_f32 v33, v38, v39
	v_cvt_pk_bf16_f32 v34, v54, v55
	v_cvt_pk_bf16_f32 v35, v56, v57
	global_store_dwordx4 v[50:51], v[32:35], off offset:256
	s_waitcnt vmcnt(13)
	s_nop 1
	v_mov_b32_e32 v32, v226
	v_mov_b32_e32 v33, v227
	v_mov_b32_e32 v34, v228
	v_mov_b32_e32 v35, v229
	v_mov_b32_e32 v36, v33
	v_mov_b32_e32 v37, v34
	v_mov_b32_e32 v33, v35
	v_pk_add_f32 v[32:33], v[36:37], v[32:33]
	v_lshlrev_b64 v[34:35], 13, v[48:49]
	v_add_f32_e32 v32, v32, v33
	ds_bpermute_b32 v33, v159, v32
	v_lshl_add_u64 v[34:35], s[10:11], 0, v[34:35]
	v_lshl_add_u64 v[34:35], v[34:35], 0, v[146:147]
	s_waitcnt lgkmcnt(0)
	v_add_f32_e32 v36, v32, v33
	ds_bpermute_b32 v37, v160, v36
	v_add_u32_e32 v32, 0xb0, v148
	v_ashrrev_i32_e32 v33, 31, v32
	s_waitcnt lgkmcnt(0)
	v_add_f32_e32 v36, v36, v37
	v_fmamk_f32 v36, v36, 0x3a800000, v157
	v_mul_f32_e32 v37, 0x4f800000, v36
	v_cmp_gt_f32_e32 vcc, s46, v36
	s_nop 1
	v_cndmask_b32_e32 v38, v36, v37, vcc
	v_sqrt_f32_e32 v39, v38
	v_lshlrev_b64 v[36:37], 6, v[32:33]
	v_lshl_add_u64 v[36:37], v[136:137], 0, v[36:37]
	v_add_u32_e32 v40, -1, v39
	v_add_u32_e32 v41, 1, v39
	v_fma_f32 v42, -v40, v39, v38
	v_fma_f32 v43, -v41, v39, v38
	v_cmp_ge_f32_e64 s[4:5], 0, v42
	s_nop 1
	v_cndmask_b32_e64 v39, v39, v40, s[4:5]
	v_cmp_lt_f32_e64 s[4:5], 0, v43
	s_nop 1
	v_cndmask_b32_e64 v39, v39, v41, s[4:5]
	v_mul_f32_e32 v40, 0x37800000, v39
	v_cndmask_b32_e32 v39, v39, v40, vcc
	v_cmp_class_f32_e32 vcc, v38, v158
	s_nop 1
	v_cndmask_b32_e32 v38, v39, v38, vcc
	v_div_scale_f32 v39, s[4:5], v38, v38, 1.0
	v_rcp_f32_e32 v40, v39
	v_div_scale_f32 v41, vcc, 1.0, v38, 1.0
	v_fma_f32 v42, -v39, v40, 1.0
	v_fmac_f32_e32 v40, v42, v40
	v_mul_f32_e32 v42, v41, v40
	v_fma_f32 v43, -v39, v42, v41
	v_fmac_f32_e32 v42, v43, v40
	v_fma_f32 v39, -v39, v42, v41
	v_div_fmas_f32 v39, v39, v40, v42
	v_div_fixup_f32 v38, v39, v38, 1.0
	v_pk_mul_f32 v[30:31], v[30:31], v[38:39] op_sel_hi:[1,0]
	v_pk_mul_f32 v[28:29], v[28:29], v[38:39] op_sel_hi:[1,0]
	v_pk_mul_f32 v[26:27], v[26:27], v[38:39] op_sel_hi:[1,0]
	v_pk_mul_f32 v[24:25], v[24:25], v[38:39] op_sel_hi:[1,0]
	v_pk_mul_f32 v[18:19], v[18:19], v[38:39] op_sel_hi:[1,0]
	v_pk_mul_f32 v[16:17], v[16:17], v[38:39] op_sel_hi:[1,0]
	v_pk_mul_f32 v[22:23], v[22:23], v[38:39] op_sel_hi:[1,0]
	v_pk_mul_f32 v[20:21], v[20:21], v[38:39] op_sel_hi:[1,0]
	v_max_f32_e32 v28, 0, v28
	v_max_f32_e32 v24, 0, v24
	v_max_f32_e32 v29, 0, v29
	v_max_f32_e32 v25, 0, v25
	v_max_f32_e32 v30, 0, v30
	v_max_f32_e32 v26, 0, v26
	v_max_f32_e32 v31, 0, v31
	v_max_f32_e32 v27, 0, v27
	v_max_f32_e32 v16, 0, v16
	v_max_f32_e32 v17, 0, v17
	v_max_f32_e32 v18, 0, v18
	v_max_f32_e32 v19, 0, v19
	v_max_f32_e32 v20, 0, v20
	v_max_f32_e32 v21, 0, v21
	v_max_f32_e32 v22, 0, v22
	v_max_f32_e32 v23, 0, v23
	v_mul_f32_e32 v28, v28, v28
	v_mul_f32_e32 v24, v24, v24
	v_mul_f32_e32 v29, v29, v29
	v_mul_f32_e32 v25, v25, v25
	v_mul_f32_e32 v30, v30, v30
	v_mul_f32_e32 v26, v26, v26
	v_mul_f32_e32 v31, v31, v31
	v_mul_f32_e32 v27, v27, v27
	v_mul_f32_e32 v38, v16, v16
	v_mul_f32_e32 v39, v17, v17
	v_mul_f32_e32 v40, v18, v18
	v_mul_f32_e32 v41, v19, v19
	v_cvt_pk_bf16_f32 v16, v28, v29
	v_cvt_pk_bf16_f32 v17, v30, v31
	v_cvt_pk_bf16_f32 v18, v24, v25
	v_cvt_pk_bf16_f32 v19, v26, v27
	v_mul_f32_e32 v20, v20, v20
	v_mul_f32_e32 v21, v21, v21
	v_mul_f32_e32 v22, v22, v22
	v_mul_f32_e32 v23, v23, v23
	global_store_dwordx4 v[34:35], v[16:19], off
	s_nop 1
	v_cvt_pk_bf16_f32 v16, v20, v21
	v_cvt_pk_bf16_f32 v17, v22, v23
	v_cvt_pk_bf16_f32 v18, v38, v39
	v_cvt_pk_bf16_f32 v19, v40, v41
	global_store_dwordx4 v[34:35], v[16:19], off offset:256
	s_waitcnt vmcnt(14)
	s_nop 1
	v_mov_b32_e32 v16, v230
	v_mov_b32_e32 v17, v231
	v_mov_b32_e32 v18, v232
	v_mov_b32_e32 v19, v233
	v_mov_b32_e32 v20, v17
	v_mov_b32_e32 v21, v18
	v_mov_b32_e32 v17, v19
	v_pk_add_f32 v[16:17], v[20:21], v[16:17]
	s_nop 0
	v_add_f32_e32 v16, v16, v17
	ds_bpermute_b32 v17, v159, v16
	s_waitcnt lgkmcnt(0)
	v_add_f32_e32 v16, v16, v17
	ds_bpermute_b32 v17, v160, v16
	s_waitcnt lgkmcnt(0)
	v_add_f32_e32 v16, v16, v17
	v_fmamk_f32 v16, v16, 0x3a800000, v157
	v_mul_f32_e32 v17, 0x4f800000, v16
	v_cmp_gt_f32_e32 vcc, s46, v16
	s_nop 1
	v_cndmask_b32_e32 v18, v16, v17, vcc
	v_sqrt_f32_e32 v19, v18
	v_lshlrev_b64 v[16:17], 13, v[32:33]
	v_lshl_add_u64 v[16:17], s[10:11], 0, v[16:17]
	v_lshl_add_u64 v[16:17], v[16:17], 0, v[146:147]
	v_add_u32_e32 v20, -1, v19
	v_add_u32_e32 v21, 1, v19
	v_fma_f32 v22, -v20, v19, v18
	v_fma_f32 v23, -v21, v19, v18
	v_cmp_ge_f32_e64 s[4:5], 0, v22
	s_nop 1
	v_cndmask_b32_e64 v19, v19, v20, s[4:5]
	v_cmp_lt_f32_e64 s[4:5], 0, v23
	s_nop 1
	v_cndmask_b32_e64 v19, v19, v21, s[4:5]
	v_mul_f32_e32 v20, 0x37800000, v19
	v_cndmask_b32_e32 v19, v19, v20, vcc
	v_cmp_class_f32_e32 vcc, v18, v158
	s_nop 1
	v_cndmask_b32_e32 v18, v19, v18, vcc
	v_div_scale_f32 v19, s[4:5], v18, v18, 1.0
	v_rcp_f32_e32 v20, v19
	v_div_scale_f32 v21, vcc, 1.0, v18, 1.0
	v_fma_f32 v22, -v19, v20, 1.0
	v_fmac_f32_e32 v20, v22, v20
	v_mul_f32_e32 v22, v21, v20
	v_fma_f32 v23, -v19, v22, v21
	v_fmac_f32_e32 v22, v23, v20
	v_fma_f32 v19, -v19, v22, v21
	v_div_fmas_f32 v19, v19, v20, v22
	v_div_fixup_f32 v18, v19, v18, 1.0
	v_pk_mul_f32 v[14:15], v[14:15], v[18:19] op_sel_hi:[1,0]
	v_pk_mul_f32 v[12:13], v[12:13], v[18:19] op_sel_hi:[1,0]
	v_pk_mul_f32 v[10:11], v[10:11], v[18:19] op_sel_hi:[1,0]
	v_pk_mul_f32 v[8:9], v[8:9], v[18:19] op_sel_hi:[1,0]
	v_pk_mul_f32 v[2:3], v[2:3], v[18:19] op_sel_hi:[1,0]
	v_pk_mul_f32 v[0:1], v[0:1], v[18:19] op_sel_hi:[1,0]
	v_pk_mul_f32 v[6:7], v[6:7], v[18:19] op_sel_hi:[1,0]
	v_pk_mul_f32 v[4:5], v[4:5], v[18:19] op_sel_hi:[1,0]
	v_max_f32_e32 v12, 0, v12
	v_max_f32_e32 v8, 0, v8
	v_max_f32_e32 v13, 0, v13
	v_max_f32_e32 v9, 0, v9
	v_max_f32_e32 v14, 0, v14
	v_max_f32_e32 v10, 0, v10
	v_max_f32_e32 v15, 0, v15
	v_max_f32_e32 v11, 0, v11
	v_max_f32_e32 v0, 0, v0
	v_max_f32_e32 v1, 0, v1
	v_max_f32_e32 v2, 0, v2
	v_max_f32_e32 v3, 0, v3
	s_andn2_b64 vcc, exec, s[0:1]
	v_max_f32_e32 v4, 0, v4
	v_max_f32_e32 v5, 0, v5
	v_max_f32_e32 v6, 0, v6
	v_max_f32_e32 v7, 0, v7
	v_mul_f32_e32 v12, v12, v12
	v_mul_f32_e32 v8, v8, v8
	v_mul_f32_e32 v13, v13, v13
	v_mul_f32_e32 v9, v9, v9
	v_mul_f32_e32 v14, v14, v14
	v_mul_f32_e32 v10, v10, v10
	v_mul_f32_e32 v15, v15, v15
	v_mul_f32_e32 v11, v11, v11
	v_mul_f32_e32 v18, v0, v0
	v_mul_f32_e32 v19, v1, v1
	v_mul_f32_e32 v20, v2, v2
	v_mul_f32_e32 v21, v3, v3
	v_cvt_pk_bf16_f32 v0, v12, v13
	v_cvt_pk_bf16_f32 v1, v14, v15
	v_cvt_pk_bf16_f32 v2, v8, v9
	v_cvt_pk_bf16_f32 v3, v10, v11
	s_mov_b64 s[0:1], -1
	v_mul_f32_e32 v4, v4, v4
	v_mul_f32_e32 v5, v5, v5
	v_mul_f32_e32 v6, v6, v6
	v_mul_f32_e32 v7, v7, v7
	global_store_dwordx4 v[16:17], v[0:3], off
	s_nop 1
	v_cvt_pk_bf16_f32 v0, v4, v5
	v_cvt_pk_bf16_f32 v1, v6, v7
	v_cvt_pk_bf16_f32 v2, v18, v19
	v_cvt_pk_bf16_f32 v3, v20, v21
	global_store_dwordx4 v[16:17], v[0:3], off offset:256
	s_cbranch_vccnz .LBB0_1241
	s_andn2_b64 vcc, exec, s[8:9]
	s_cbranch_vccnz .LBB0_1240
	s_barrier
	s_branch .LBB0_1240

	.amdhsa_kernel _Z10fwd_kernel4Args
		.amdhsa_group_segment_fixed_size 0
		.amdhsa_private_segment_fixed_size 0
		.amdhsa_kernarg_size 416
		.amdhsa_user_sgpr_count 2
		.amdhsa_user_sgpr_dispatch_ptr 0
		.amdhsa_user_sgpr_queue_ptr 0
		.amdhsa_user_sgpr_kernarg_segment_ptr 1
		.amdhsa_user_sgpr_dispatch_id 0
		.amdhsa_user_sgpr_kernarg_preload_length 0
		.amdhsa_user_sgpr_kernarg_preload_offset 0
		.amdhsa_user_sgpr_private_segment_size 0
		.amdhsa_uses_dynamic_stack 0
		.amdhsa_enable_private_segment 0
		.amdhsa_system_sgpr_workgroup_id_x 1
		.amdhsa_system_sgpr_workgroup_id_y 0
		.amdhsa_system_sgpr_workgroup_id_z 0
		.amdhsa_system_sgpr_workgroup_info 0
		.amdhsa_system_vgpr_workitem_id 2
		.amdhsa_next_free_vgpr 255
		.amdhsa_next_free_sgpr 100
		.amdhsa_accum_offset 256
		.amdhsa_reserve_vcc 1
		.amdhsa_float_round_mode_32 0
		.amdhsa_float_round_mode_16_64 0
		.amdhsa_float_denorm_mode_32 3
		.amdhsa_float_denorm_mode_16_64 3
		.amdhsa_dx10_clamp 1
		.amdhsa_ieee_mode 1
		.amdhsa_fp16_overflow 0
		.amdhsa_tg_split 0
		.amdhsa_exception_fp_ieee_invalid_op 0
		.amdhsa_exception_fp_denorm_src 0
		.amdhsa_exception_fp_ieee_div_zero 0
		.amdhsa_exception_fp_ieee_overflow 0
		.amdhsa_exception_fp_ieee_underflow 0
		.amdhsa_exception_fp_ieee_inexact 0
		.amdhsa_exception_int_div_zero 0
	.end_amdhsa_kernel

amdhsa.kernels:
  - .agpr_count:     0
    .args:
      - .offset:         0
        .size:           160
        .value_kind:     by_value
      - .offset:         160
        .size:           4
        .value_kind:     hidden_block_count_x
      - .offset:         164
        .size:           4
        .value_kind:     hidden_block_count_y
      - .offset:         168
        .size:           4
        .value_kind:     hidden_block_count_z
      - .offset:         172
        .size:           2
        .value_kind:     hidden_group_size_x
      - .offset:         174
        .size:           2
        .value_kind:     hidden_group_size_y
      - .offset:         176
        .size:           2
        .value_kind:     hidden_group_size_z
      - .offset:         178
        .size:           2
        .value_kind:     hidden_remainder_x
      - .offset:         180
        .size:           2
        .value_kind:     hidden_remainder_y
      - .offset:         182
        .size:           2
        .value_kind:     hidden_remainder_z
      - .offset:         200
        .size:           8
        .value_kind:     hidden_global_offset_x
      - .offset:         208
        .size:           8
        .value_kind:     hidden_global_offset_y
      - .offset:         216
        .size:           8
        .value_kind:     hidden_global_offset_z
      - .offset:         224
        .size:           2
        .value_kind:     hidden_grid_dims
      - .offset:         248
        .size:           8
        .value_kind:     hidden_multigrid_sync_arg
      - .offset:         280
        .size:           4
        .value_kind:     hidden_dynamic_lds_size
    .group_segment_fixed_size: 0
    .kernarg_segment_align: 8
    .kernarg_segment_size: 416
    .language:       OpenCL C
    .language_version:
      - 2
      - 0
    .max_flat_workgroup_size: 512
    .name:           _Z10fwd_kernel4Args
    .private_segment_fixed_size: 0
    .sgpr_count:     106
    .sgpr_spill_count: 60
    .symbol:         _Z10fwd_kernel4Args.kd
    .uniform_work_group_size: 1
    .uses_dynamic_stack: false
    .vgpr_count:     255
    .vgpr_spill_count: 0
    .wavefront_size: 64
